# attention V DMAs: M0 write hoisted one instruction earlier, s_nop pad removed (one issue slot per DMA)
# speedup vs baseline: 1.0014x; 1.0014x over previous
.LBB0_520:
	s_ashr_i32 s53, s52, 31
	s_lshl_b64 s[4:5], s[52:53], 17
	s_add_u32 s54, s44, s4
	s_addc_u32 s55, s45, s5
	s_and_b64 s[4:5], s[0:1], exec
	s_cselect_b32 s59, s55, s61
	s_cselect_b32 s58, s54, s60
	s_ashr_i32 s15, s14, 31
	s_lshl_b64 s[4:5], s[14:15], 17
	s_add_u32 s84, s3, s4
	s_addc_u32 s85, s25, s5
	s_and_b64 s[4:5], s[0:1], exec
	s_cselect_b32 s5, s85, s57
	s_cselect_b32 s4, s84, s56
	s_add_i32 s17, 0, 0x10000
	s_add_i32 s67, 0, 0x14000
	v_add_u32_e32 v176, s17, v224
	v_add_u32_e32 v177, s67, v224
	ds_read_b128 v[0:3], v176
	ds_read_b128 v[4:7], v176 offset:1024
	ds_read_b128 v[8:11], v176 offset:2048
	ds_read_b128 v[14:17], v176 offset:3072
	ds_read_b128 v[18:21], v177
	ds_read_b128 v[22:25], v177 offset:1024
	ds_read_b128 v[26:29], v177 offset:2048
	ds_read_b128 v[30:33], v177 offset:3072
	s_add_u32 vcc_lo, s60, 0x10080
	s_addc_u32 vcc_hi, s61, 0
	s_add_i32 s35, s16, 0xc000
	v_lshl_add_u64 v[66:67], vcc, 0, v[12:13]
	s_mov_b32 m0, s35
	s_add_i32 s15, s16, 0xe000
	ds_read_b128 v[34:37], v225
	ds_read_b128 v[38:41], v225 offset:1024
	ds_read_b128 v[42:45], v225 offset:2048
	ds_read_b128 v[46:49], v225 offset:3072
	ds_read_b128 v[50:53], v225 offset:4096
	ds_read_b128 v[54:57], v225 offset:5120
	ds_read_b128 v[58:61], v225 offset:6144
	ds_read_b128 v[62:65], v225 offset:7168
	global_load_lds_dwordx4 v[66:67], off
	s_mov_b32 m0, s15
	v_lshl_add_u64 v[66:67], vcc, 0, v[154:155]
	global_load_lds_dwordx4 v[66:67], off
	s_waitcnt vmcnt(8)
	s_waitcnt lgkmcnt(0)
	s_barrier
	s_setprio 1
	s_waitcnt lgkmcnt(0)
	v_mfma_f32_16x16x32_bf16 v[66:69], v[0:3], v[34:37], 0
	v_mfma_f32_16x16x32_bf16 v[70:73], v[8:11], v[34:37], 0
	v_mfma_f32_16x16x32_bf16 v[74:77], v[0:3], v[42:45], 0
	v_mfma_f32_16x16x32_bf16 v[78:81], v[8:11], v[42:45], 0
	v_mfma_f32_16x16x32_bf16 v[82:85], v[0:3], v[50:53], 0
	v_mfma_f32_16x16x32_bf16 v[86:89], v[8:11], v[50:53], 0
	v_mfma_f32_16x16x32_bf16 v[90:93], v[0:3], v[58:61], 0
	v_mfma_f32_16x16x32_bf16 v[94:97], v[8:11], v[58:61], 0
	v_mfma_f32_16x16x32_bf16 v[66:69], v[4:7], v[38:41], v[66:69]
	v_mfma_f32_16x16x32_bf16 v[70:73], v[14:17], v[38:41], v[70:73]
	v_mfma_f32_16x16x32_bf16 v[74:77], v[4:7], v[46:49], v[74:77]
	v_mfma_f32_16x16x32_bf16 v[78:81], v[14:17], v[46:49], v[78:81]
	v_mfma_f32_16x16x32_bf16 v[82:85], v[4:7], v[54:57], v[82:85]
	v_mfma_f32_16x16x32_bf16 v[86:89], v[14:17], v[54:57], v[86:89]
	v_mfma_f32_16x16x32_bf16 v[90:93], v[4:7], v[62:65], v[90:93]
	v_mfma_f32_16x16x32_bf16 v[94:97], v[14:17], v[62:65], v[94:97]
	s_setprio 0
	s_setprio 1
	v_mfma_f32_16x16x32_bf16 v[98:101], v[18:21], v[34:37], 0
	v_mfma_f32_16x16x32_bf16 v[34:37], v[26:29], v[34:37], 0
	v_mfma_f32_16x16x32_bf16 v[98:101], v[22:25], v[38:41], v[98:101]
	v_mfma_f32_16x16x32_bf16 v[34:37], v[30:33], v[38:41], v[34:37]
	v_mfma_f32_16x16x32_bf16 v[38:41], v[18:21], v[42:45], 0
	v_mfma_f32_16x16x32_bf16 v[42:45], v[26:29], v[42:45], 0
	v_mfma_f32_16x16x32_bf16 v[38:41], v[22:25], v[46:49], v[38:41]
	v_mfma_f32_16x16x32_bf16 v[42:45], v[30:33], v[46:49], v[42:45]
	v_mfma_f32_16x16x32_bf16 v[46:49], v[18:21], v[50:53], 0
	v_mfma_f32_16x16x32_bf16 v[50:53], v[26:29], v[50:53], 0
	v_mfma_f32_16x16x32_bf16 v[46:49], v[22:25], v[54:57], v[46:49]
	v_mfma_f32_16x16x32_bf16 v[50:53], v[30:33], v[54:57], v[50:53]
	v_mfma_f32_16x16x32_bf16 v[54:57], v[18:21], v[58:61], 0
	v_mfma_f32_16x16x32_bf16 v[58:61], v[26:29], v[58:61], 0
	v_mfma_f32_16x16x32_bf16 v[54:57], v[22:25], v[62:65], v[54:57]
	v_mfma_f32_16x16x32_bf16 v[58:61], v[30:33], v[62:65], v[58:61]
	s_setprio 0
	s_barrier
	s_add_i32 vcc_lo, s17, s34
	v_lshl_add_u64 v[164:165], s[56:57], 0, v[12:13]
	s_mov_b64 s[6:7], 0x100
	s_add_i32 s53, vcc_lo, 0x2000
	v_lshl_add_u64 v[130:131], v[164:165], 0, s[6:7]
	s_mov_b32 m0, vcc_lo
	v_lshl_add_u64 v[168:169], s[56:57], 0, v[154:155]
	s_add_u32 s26, s56, 0x10100
	ds_read_b128 v[62:65], v225 offset:16384
	ds_read_b128 v[102:105], v225 offset:17408
	ds_read_b128 v[106:109], v225 offset:18432
	ds_read_b128 v[110:113], v225 offset:19456
	ds_read_b128 v[114:117], v225 offset:20480
	ds_read_b128 v[118:121], v225 offset:21504
	ds_read_b128 v[122:125], v225 offset:22528
	ds_read_b128 v[126:129], v225 offset:23552
	global_load_lds_dwordx4 v[130:131], off
	v_lshl_add_u64 v[130:131], v[168:169], 0, s[6:7]
	s_mov_b32 m0, s53
	s_addc_u32 s27, s57, 0
	s_add_i32 s67, s67, s34
	global_load_lds_dwordx4 v[130:131], off
	v_lshl_add_u64 v[130:131], s[26:27], 0, v[12:13]
	s_mov_b32 m0, s67
	s_add_i32 s74, s67, 0x2000
	global_load_lds_dwordx4 v[130:131], off
	v_lshl_add_u64 v[130:131], s[26:27], 0, v[154:155]
	s_mov_b32 m0, s74
	v_lshl_add_u64 v[170:171], s[60:61], 0, v[12:13]
	global_load_lds_dwordx4 v[130:131], off
	v_lshl_add_u64 v[130:131], v[170:171], 0, s[6:7]
	s_mov_b32 m0, s16
	v_lshl_add_u64 v[172:173], s[60:61], 0, v[154:155]
	global_load_lds_dwordx4 v[130:131], off
	v_lshl_add_u64 v[130:131], v[172:173], 0, s[6:7]
	s_mov_b32 m0, s38
	s_nop 0
	global_load_lds_dwordx4 v[130:131], off
	s_waitcnt vmcnt(8)
	s_waitcnt lgkmcnt(0)
	s_barrier
	s_setprio 1
	s_waitcnt lgkmcnt(0)
	v_mfma_f32_16x16x32_bf16 v[130:133], v[0:3], v[62:65], 0
	v_mfma_f32_16x16x32_bf16 v[138:141], v[0:3], v[106:109], 0
	v_mfma_f32_16x16x32_bf16 v[146:149], v[0:3], v[114:117], 0
	v_mfma_f32_16x16x32_bf16 v[0:3], v[0:3], v[122:125], 0
	v_mfma_f32_16x16x32_bf16 v[130:133], v[4:7], v[102:105], v[130:133]
	v_mfma_f32_16x16x32_bf16 v[138:141], v[4:7], v[110:113], v[138:141]
	v_mfma_f32_16x16x32_bf16 v[146:149], v[4:7], v[118:121], v[146:149]
	v_mfma_f32_16x16x32_bf16 v[150:153], v[8:11], v[114:117], 0
	v_mfma_f32_16x16x32_bf16 v[0:3], v[4:7], v[126:129], v[0:3]
	v_mfma_f32_16x16x32_bf16 v[4:7], v[8:11], v[122:125], 0
	v_mfma_f32_16x16x32_bf16 v[134:137], v[8:11], v[62:65], 0
	v_mfma_f32_16x16x32_bf16 v[142:145], v[8:11], v[106:109], 0
	v_mfma_f32_16x16x32_bf16 v[150:153], v[14:17], v[118:121], v[150:153]
	v_mfma_f32_16x16x32_bf16 v[4:7], v[14:17], v[126:129], v[4:7]
	v_mfma_f32_16x16x32_bf16 v[134:137], v[14:17], v[102:105], v[134:137]
	v_mfma_f32_16x16x32_bf16 v[142:145], v[14:17], v[110:113], v[142:145]
	s_setprio 0
	s_setprio 1
	v_mfma_f32_16x16x32_bf16 v[8:11], v[18:21], v[62:65], 0
	v_mfma_f32_16x16x32_bf16 v[14:17], v[26:29], v[62:65], 0
	v_mfma_f32_16x16x32_bf16 v[8:11], v[22:25], v[102:105], v[8:11]
	v_mfma_f32_16x16x32_bf16 v[14:17], v[30:33], v[102:105], v[14:17]
	v_mfma_f32_16x16x32_bf16 v[62:65], v[18:21], v[106:109], 0
	v_mfma_f32_16x16x32_bf16 v[102:105], v[26:29], v[106:109], 0
	v_mfma_f32_16x16x32_bf16 v[106:109], v[18:21], v[114:117], 0
	v_mfma_f32_16x16x32_bf16 v[18:21], v[18:21], v[122:125], 0
	v_mfma_f32_16x16x32_bf16 v[62:65], v[22:25], v[110:113], v[62:65]
	v_mfma_f32_16x16x32_bf16 v[106:109], v[22:25], v[118:121], v[106:109]
	v_mfma_f32_16x16x32_bf16 v[18:21], v[22:25], v[126:129], v[18:21]
	v_mfma_f32_16x16x32_bf16 v[22:25], v[26:29], v[122:125], 0
	v_mfma_f32_16x16x32_bf16 v[102:105], v[30:33], v[110:113], v[102:105]
	v_mfma_f32_16x16x32_bf16 v[110:113], v[26:29], v[114:117], 0
	v_mfma_f32_16x16x32_bf16 v[22:25], v[30:33], v[126:129], v[22:25]
	v_mfma_f32_16x16x32_bf16 v[110:113], v[30:33], v[118:121], v[110:113]
	s_setprio 0
	s_barrier
	s_add_i32 s17, 0, 0x18000
	s_add_i32 s6, 0, 0x1c000
	v_add_u32_e32 v214, s17, v224
	v_add_u32_e32 v215, s6, v224
	ds_read_b128 v[26:29], v214
	ds_read_b128 v[30:33], v214 offset:1024
	ds_read_b128 v[114:117], v214 offset:2048
	ds_read_b128 v[118:121], v214 offset:3072
	ds_read_b128 v[122:125], v215
	ds_read_b128 v[126:129], v215 offset:1024
	ds_read_b128 v[156:159], v215 offset:2048
	ds_read_b128 v[160:163], v215 offset:3072
	s_add_u32 s26, s60, 0x10100
	s_addc_u32 s27, s61, 0
	s_mov_b32 m0, s39
	v_lshl_add_u64 v[174:175], s[26:27], 0, v[12:13]
	ds_read_b128 v[178:181], v225 offset:32768
	ds_read_b128 v[182:185], v225 offset:33792
	ds_read_b128 v[186:189], v225 offset:34816
	ds_read_b128 v[190:193], v225 offset:35840
	ds_read_b128 v[194:197], v225 offset:36864
	ds_read_b128 v[198:201], v225 offset:37888
	ds_read_b128 v[202:205], v225 offset:38912
	ds_read_b128 v[206:209], v225 offset:39936
	global_load_lds_dwordx4 v[174:175], off
	v_lshl_add_u64 v[174:175], s[26:27], 0, v[154:155]
	s_mov_b32 m0, s40
	s_nop 0
	global_load_lds_dwordx4 v[174:175], off
	s_waitcnt vmcnt(8)
	s_waitcnt lgkmcnt(0)
	s_barrier
	s_setprio 1
	s_waitcnt lgkmcnt(0)
	v_mfma_f32_16x16x32_bf16 v[66:69], v[26:29], v[178:181], v[66:69]
	v_mfma_f32_16x16x32_bf16 v[70:73], v[114:117], v[178:181], v[70:73]
	v_mfma_f32_16x16x32_bf16 v[74:77], v[26:29], v[186:189], v[74:77]
	v_mfma_f32_16x16x32_bf16 v[78:81], v[114:117], v[186:189], v[78:81]
	v_mfma_f32_16x16x32_bf16 v[82:85], v[26:29], v[194:197], v[82:85]
	v_mfma_f32_16x16x32_bf16 v[86:89], v[114:117], v[194:197], v[86:89]
	v_mfma_f32_16x16x32_bf16 v[90:93], v[26:29], v[202:205], v[90:93]
	v_mfma_f32_16x16x32_bf16 v[94:97], v[114:117], v[202:205], v[94:97]
	v_mfma_f32_16x16x32_bf16 v[66:69], v[30:33], v[182:185], v[66:69]
	v_mfma_f32_16x16x32_bf16 v[70:73], v[118:121], v[182:185], v[70:73]
	v_mfma_f32_16x16x32_bf16 v[74:77], v[30:33], v[190:193], v[74:77]
	v_mfma_f32_16x16x32_bf16 v[78:81], v[118:121], v[190:193], v[78:81]
	v_mfma_f32_16x16x32_bf16 v[82:85], v[30:33], v[198:201], v[82:85]
	v_mfma_f32_16x16x32_bf16 v[86:89], v[118:121], v[198:201], v[86:89]
	v_mfma_f32_16x16x32_bf16 v[90:93], v[30:33], v[206:209], v[90:93]
	v_mfma_f32_16x16x32_bf16 v[94:97], v[118:121], v[206:209], v[94:97]
	s_setprio 0
	s_setprio 1
	v_mfma_f32_16x16x32_bf16 v[98:101], v[122:125], v[178:181], v[98:101]
	v_mfma_f32_16x16x32_bf16 v[34:37], v[156:159], v[178:181], v[34:37]
	v_mfma_f32_16x16x32_bf16 v[38:41], v[122:125], v[186:189], v[38:41]
	v_mfma_f32_16x16x32_bf16 v[42:45], v[156:159], v[186:189], v[42:45]
	v_mfma_f32_16x16x32_bf16 v[46:49], v[122:125], v[194:197], v[46:49]
	v_mfma_f32_16x16x32_bf16 v[50:53], v[156:159], v[194:197], v[50:53]
	v_mfma_f32_16x16x32_bf16 v[54:57], v[122:125], v[202:205], v[54:57]
	v_mfma_f32_16x16x32_bf16 v[58:61], v[156:159], v[202:205], v[58:61]
	v_mfma_f32_16x16x32_bf16 v[98:101], v[126:129], v[182:185], v[98:101]
	v_mfma_f32_16x16x32_bf16 v[34:37], v[160:163], v[182:185], v[34:37]
	v_mfma_f32_16x16x32_bf16 v[38:41], v[126:129], v[190:193], v[38:41]
	v_mfma_f32_16x16x32_bf16 v[42:45], v[160:163], v[190:193], v[42:45]
	v_mfma_f32_16x16x32_bf16 v[46:49], v[126:129], v[198:201], v[46:49]
	v_mfma_f32_16x16x32_bf16 v[50:53], v[160:163], v[198:201], v[50:53]
	v_mfma_f32_16x16x32_bf16 v[54:57], v[126:129], v[206:209], v[54:57]
	v_mfma_f32_16x16x32_bf16 v[58:61], v[160:163], v[206:209], v[58:61]
	s_setprio 0
	s_barrier
	s_add_i32 s17, s17, s34
	s_mov_b64 s[76:77], 0x180
	s_add_i32 vcc_hi, s17, 0x2000
	v_lshl_add_u64 v[164:165], v[164:165], 0, s[76:77]
	s_mov_b32 m0, s17
	s_add_u32 s26, s56, 0x10180
	ds_read_b128 v[178:181], v225 offset:49152
	ds_read_b128 v[182:185], v225 offset:50176
	ds_read_b128 v[186:189], v225 offset:51200
	ds_read_b128 v[190:193], v225 offset:52224
	ds_read_b128 v[194:197], v225 offset:53248
	ds_read_b128 v[198:201], v225 offset:54272
	ds_read_b128 v[202:205], v225 offset:55296
	ds_read_b128 v[206:209], v225 offset:56320
	global_load_lds_dwordx4 v[164:165], off
	v_lshl_add_u64 v[164:165], v[168:169], 0, s[76:77]
	s_mov_b32 m0, vcc_hi
	s_addc_u32 s27, s57, 0
	s_add_i32 s6, s6, s34
	global_load_lds_dwordx4 v[164:165], off
	v_lshl_add_u64 v[164:165], s[26:27], 0, v[12:13]
	s_mov_b32 m0, s6
	s_add_i32 s7, s6, 0x2000
	global_load_lds_dwordx4 v[164:165], off
	v_lshl_add_u64 v[164:165], s[26:27], 0, v[154:155]
	s_mov_b32 m0, s7
	s_nop 0
	global_load_lds_dwordx4 v[164:165], off
	v_lshl_add_u64 v[164:165], v[170:171], 0, s[76:77]
	s_mov_b32 m0, s63
	s_nop 0
	global_load_lds_dwordx4 v[164:165], off
	v_lshl_add_u64 v[164:165], v[172:173], 0, s[76:77]
	s_mov_b32 m0, s64
	s_nop 0
	global_load_lds_dwordx4 v[164:165], off
	s_waitcnt vmcnt(8)
	s_waitcnt lgkmcnt(0)
	s_barrier
	s_setprio 1
	s_waitcnt lgkmcnt(0)
	v_mfma_f32_16x16x32_bf16 v[146:149], v[26:29], v[194:197], v[146:149]
	v_mfma_f32_16x16x32_bf16 v[150:153], v[114:117], v[194:197], v[150:153]
	v_mfma_f32_16x16x32_bf16 v[0:3], v[26:29], v[202:205], v[0:3]
	v_mfma_f32_16x16x32_bf16 v[4:7], v[114:117], v[202:205], v[4:7]
	v_mfma_f32_16x16x32_bf16 v[130:133], v[26:29], v[178:181], v[130:133]
	v_mfma_f32_16x16x32_bf16 v[134:137], v[114:117], v[178:181], v[134:137]
	v_mfma_f32_16x16x32_bf16 v[138:141], v[26:29], v[186:189], v[138:141]
	v_mfma_f32_16x16x32_bf16 v[142:145], v[114:117], v[186:189], v[142:145]
	v_mfma_f32_16x16x32_bf16 v[146:149], v[30:33], v[198:201], v[146:149]
	v_mfma_f32_16x16x32_bf16 v[150:153], v[118:121], v[198:201], v[150:153]
	v_mfma_f32_16x16x32_bf16 v[0:3], v[30:33], v[206:209], v[0:3]
	v_mfma_f32_16x16x32_bf16 v[4:7], v[118:121], v[206:209], v[4:7]
	v_mfma_f32_16x16x32_bf16 v[130:133], v[30:33], v[182:185], v[130:133]
	v_mfma_f32_16x16x32_bf16 v[134:137], v[118:121], v[182:185], v[134:137]
	v_mfma_f32_16x16x32_bf16 v[138:141], v[30:33], v[190:193], v[138:141]
	v_mfma_f32_16x16x32_bf16 v[142:145], v[118:121], v[190:193], v[142:145]
	s_setprio 0
	s_setprio 1
	v_mfma_f32_16x16x32_bf16 v[8:11], v[122:125], v[178:181], v[8:11]
	v_mfma_f32_16x16x32_bf16 v[14:17], v[156:159], v[178:181], v[14:17]
	v_mfma_f32_16x16x32_bf16 v[26:29], v[122:125], v[186:189], v[62:65]
	v_mfma_f32_16x16x32_bf16 v[30:33], v[156:159], v[186:189], v[102:105]
	v_mfma_f32_16x16x32_bf16 v[62:65], v[122:125], v[194:197], v[106:109]
	v_mfma_f32_16x16x32_bf16 v[102:105], v[156:159], v[194:197], v[110:113]
	v_mfma_f32_16x16x32_bf16 v[18:21], v[122:125], v[202:205], v[18:21]
	v_mfma_f32_16x16x32_bf16 v[22:25], v[156:159], v[202:205], v[22:25]
	v_mfma_f32_16x16x32_bf16 v[8:11], v[126:129], v[182:185], v[8:11]
	v_mfma_f32_16x16x32_bf16 v[14:17], v[160:163], v[182:185], v[14:17]
	v_mfma_f32_16x16x32_bf16 v[26:29], v[126:129], v[190:193], v[26:29]
	v_mfma_f32_16x16x32_bf16 v[30:33], v[160:163], v[190:193], v[30:33]
	v_mfma_f32_16x16x32_bf16 v[62:65], v[126:129], v[198:201], v[62:65]
	v_mfma_f32_16x16x32_bf16 v[102:105], v[160:163], v[198:201], v[102:105]
	v_mfma_f32_16x16x32_bf16 v[18:21], v[126:129], v[206:209], v[18:21]
	v_mfma_f32_16x16x32_bf16 v[22:25], v[160:163], v[206:209], v[22:25]
	s_setprio 0
	s_barrier
	ds_read_b128 v[106:109], v176
	ds_read_b128 v[110:113], v176 offset:1024
	ds_read_b128 v[114:117], v176 offset:2048
	ds_read_b128 v[118:121], v176 offset:3072
	ds_read_b128 v[122:125], v177
	ds_read_b128 v[126:129], v177 offset:1024
	ds_read_b128 v[156:159], v177 offset:2048
	ds_read_b128 v[160:163], v177 offset:3072
	s_add_u32 s26, s60, 0x10180
	s_addc_u32 s27, s61, 0
	s_mov_b32 m0, s35
	v_lshl_add_u64 v[164:165], s[26:27], 0, v[12:13]
	ds_read_b128 v[178:181], v225
	ds_read_b128 v[182:185], v225 offset:1024
	ds_read_b128 v[186:189], v225 offset:2048
	ds_read_b128 v[190:193], v225 offset:3072
	ds_read_b128 v[194:197], v225 offset:4096
	ds_read_b128 v[198:201], v225 offset:5120
	ds_read_b128 v[202:205], v225 offset:6144
	ds_read_b128 v[206:209], v225 offset:7168
	global_load_lds_dwordx4 v[164:165], off
	s_mov_b32 m0, s15
	v_lshl_add_u64 v[164:165], s[26:27], 0, v[154:155]
	global_load_lds_dwordx4 v[164:165], off
	s_waitcnt vmcnt(8)
	s_waitcnt lgkmcnt(0)
	s_barrier
	s_setprio 1
	s_waitcnt lgkmcnt(0)
	v_mfma_f32_16x16x32_bf16 v[66:69], v[106:109], v[178:181], v[66:69]
	v_mfma_f32_16x16x32_bf16 v[70:73], v[114:117], v[178:181], v[70:73]
	v_mfma_f32_16x16x32_bf16 v[74:77], v[106:109], v[186:189], v[74:77]
	v_mfma_f32_16x16x32_bf16 v[78:81], v[114:117], v[186:189], v[78:81]
	v_mfma_f32_16x16x32_bf16 v[82:85], v[106:109], v[194:197], v[82:85]
	v_mfma_f32_16x16x32_bf16 v[86:89], v[114:117], v[194:197], v[86:89]
	v_mfma_f32_16x16x32_bf16 v[90:93], v[106:109], v[202:205], v[90:93]
	v_mfma_f32_16x16x32_bf16 v[94:97], v[114:117], v[202:205], v[94:97]
	v_mfma_f32_16x16x32_bf16 v[66:69], v[110:113], v[182:185], v[66:69]
	v_mfma_f32_16x16x32_bf16 v[70:73], v[118:121], v[182:185], v[70:73]
	v_mfma_f32_16x16x32_bf16 v[74:77], v[110:113], v[190:193], v[74:77]
	v_mfma_f32_16x16x32_bf16 v[78:81], v[118:121], v[190:193], v[78:81]
	v_mfma_f32_16x16x32_bf16 v[82:85], v[110:113], v[198:201], v[82:85]
	v_mfma_f32_16x16x32_bf16 v[86:89], v[118:121], v[198:201], v[86:89]
	v_mfma_f32_16x16x32_bf16 v[90:93], v[110:113], v[206:209], v[90:93]
	v_mfma_f32_16x16x32_bf16 v[94:97], v[118:121], v[206:209], v[94:97]
	s_setprio 0
	s_setprio 1
	v_mfma_f32_16x16x32_bf16 v[50:53], v[156:159], v[194:197], v[50:53]
	v_mfma_f32_16x16x32_bf16 v[98:101], v[122:125], v[178:181], v[98:101]
	v_mfma_f32_16x16x32_bf16 v[34:37], v[156:159], v[178:181], v[34:37]
	v_mfma_f32_16x16x32_bf16 v[38:41], v[122:125], v[186:189], v[38:41]
	v_mfma_f32_16x16x32_bf16 v[42:45], v[156:159], v[186:189], v[42:45]
	v_mfma_f32_16x16x32_bf16 v[46:49], v[122:125], v[194:197], v[46:49]
	v_mfma_f32_16x16x32_bf16 v[178:181], v[160:163], v[198:201], v[50:53]
	v_mfma_f32_16x16x32_bf16 v[50:53], v[122:125], v[202:205], v[54:57]
	v_mfma_f32_16x16x32_bf16 v[210:213], v[126:129], v[182:185], v[98:101]
	v_mfma_f32_16x16x32_bf16 v[34:37], v[160:163], v[182:185], v[34:37]
	v_mfma_f32_16x16x32_bf16 v[38:41], v[126:129], v[190:193], v[38:41]
	v_mfma_f32_16x16x32_bf16 v[42:45], v[160:163], v[190:193], v[42:45]
	v_mfma_f32_16x16x32_bf16 v[46:49], v[126:129], v[198:201], v[46:49]
	v_mfma_f32_16x16x32_bf16 v[182:185], v[126:129], v[206:209], v[50:53]
	v_mfma_f32_16x16x32_bf16 v[50:53], v[156:159], v[202:205], v[58:61]
	v_mfma_f32_16x16x32_bf16 v[186:189], v[160:163], v[206:209], v[50:53]
	s_setprio 0
	s_barrier
	s_mov_b32 m0, vcc_lo
	v_lshl_add_u64 v[164:165], s[4:5], 0, v[12:13]
	s_add_u32 s26, s4, 0x10000
	s_nop 1
	ds_read_b128 v[50:53], v225 offset:16384
	ds_read_b128 v[54:57], v225 offset:17408
	ds_read_b128 v[58:61], v225 offset:18432
	ds_read_b128 v[98:101], v225 offset:19456
	ds_read_b128 v[190:193], v225 offset:20480
	ds_read_b128 v[194:197], v225 offset:21504
	ds_read_b128 v[198:201], v225 offset:22528
	ds_read_b128 v[202:205], v225 offset:23552
	global_load_lds_dwordx4 v[164:165], off
	v_lshl_add_u64 v[250:251], s[4:5], 0, v[154:155]
	s_mov_b32 m0, s53
	s_addc_u32 s27, s5, 0
	global_load_lds_dwordx4 v[250:251], off
	v_lshl_add_u64 v[168:169], s[26:27], 0, v[12:13]
	s_mov_b32 m0, s67
	v_lshl_add_u64 v[218:219], s[58:59], 0, v[12:13]
	global_load_lds_dwordx4 v[168:169], off
	v_lshl_add_u64 v[168:169], s[26:27], 0, v[154:155]
	s_mov_b32 m0, s74
	v_lshl_add_u64 v[176:177], s[58:59], 0, v[154:155]
	global_load_lds_dwordx4 v[168:169], off
	s_mov_b32 m0, s16
	s_nop 0
	global_load_lds_dwordx4 v[218:219], off
	s_mov_b32 m0, s38
	s_nop 0
	global_load_lds_dwordx4 v[176:177], off
	s_waitcnt vmcnt(8)
	s_waitcnt lgkmcnt(0)
	s_barrier
	s_setprio 1
	s_waitcnt lgkmcnt(0)
	v_mfma_f32_16x16x32_bf16 v[146:149], v[106:109], v[190:193], v[146:149]
	v_mfma_f32_16x16x32_bf16 v[0:3], v[106:109], v[198:201], v[0:3]
	v_mfma_f32_16x16x32_bf16 v[4:7], v[114:117], v[198:201], v[4:7]
	v_mfma_f32_16x16x32_bf16 v[130:133], v[106:109], v[50:53], v[130:133]
	v_mfma_f32_16x16x32_bf16 v[134:137], v[114:117], v[50:53], v[134:137]
	v_mfma_f32_16x16x32_bf16 v[138:141], v[106:109], v[58:61], v[138:141]
	v_mfma_f32_16x16x32_bf16 v[142:145], v[114:117], v[58:61], v[142:145]
	v_mfma_f32_16x16x32_bf16 v[206:209], v[110:113], v[194:197], v[146:149]
	v_mfma_f32_16x16x32_bf16 v[146:149], v[114:117], v[190:193], v[150:153]
	v_mfma_f32_16x16x32_bf16 v[0:3], v[110:113], v[202:205], v[0:3]
	v_mfma_f32_16x16x32_bf16 v[4:7], v[118:121], v[202:205], v[4:7]
	v_mfma_f32_16x16x32_bf16 v[130:133], v[110:113], v[54:57], v[130:133]
	v_mfma_f32_16x16x32_bf16 v[134:137], v[118:121], v[54:57], v[134:137]
	v_mfma_f32_16x16x32_bf16 v[138:141], v[110:113], v[98:101], v[138:141]
	v_mfma_f32_16x16x32_bf16 v[142:145], v[118:121], v[98:101], v[142:145]
	v_mfma_f32_16x16x32_bf16 v[226:229], v[118:121], v[194:197], v[146:149]
	s_setprio 0
	s_setprio 1
	v_mfma_f32_16x16x32_bf16 v[26:29], v[122:125], v[58:61], v[26:29]
	v_mfma_f32_16x16x32_bf16 v[106:109], v[126:129], v[98:101], v[26:29]
	v_mfma_f32_16x16x32_bf16 v[26:29], v[156:159], v[58:61], v[30:33]
	v_mfma_f32_16x16x32_bf16 v[110:113], v[160:163], v[98:101], v[26:29]
	v_mfma_f32_16x16x32_bf16 v[26:29], v[122:125], v[190:193], v[62:65]
	v_mfma_f32_16x16x32_bf16 v[8:11], v[122:125], v[50:53], v[8:11]
	v_mfma_f32_16x16x32_bf16 v[14:17], v[156:159], v[50:53], v[14:17]
	v_mfma_f32_16x16x32_bf16 v[230:233], v[126:129], v[194:197], v[26:29]
	v_mfma_f32_16x16x32_bf16 v[26:29], v[156:159], v[190:193], v[102:105]
	v_mfma_f32_16x16x32_bf16 v[18:21], v[122:125], v[198:201], v[18:21]
	v_mfma_f32_16x16x32_bf16 v[8:11], v[126:129], v[54:57], v[8:11]
	v_mfma_f32_16x16x32_bf16 v[14:17], v[160:163], v[54:57], v[14:17]
	v_mfma_f32_16x16x32_bf16 v[190:193], v[160:163], v[194:197], v[26:29]
	v_mfma_f32_16x16x32_bf16 v[194:197], v[126:129], v[202:205], v[18:21]
	v_mfma_f32_16x16x32_bf16 v[18:21], v[156:159], v[198:201], v[22:25]
	v_mfma_f32_16x16x32_bf16 v[156:159], v[160:163], v[202:205], v[18:21]
	s_setprio 0
	s_barrier
	s_nop 4
	ds_read_b128 v[18:21], v214
	ds_read_b128 v[22:25], v214 offset:1024
	ds_read_b128 v[26:29], v214 offset:2048
	ds_read_b128 v[30:33], v214 offset:3072
	ds_read_b128 v[160:163], v215
	ds_read_b128 v[198:201], v215 offset:1024
	ds_read_b128 v[202:205], v215 offset:2048
	ds_read_b128 v[234:237], v215 offset:3072
	s_add_u32 s26, s58, 0x10000
	s_addc_u32 s27, s59, 0
	s_mov_b32 m0, s39
	v_lshl_add_u64 v[58:59], s[26:27], 0, v[12:13]
	ds_read_b128 v[50:53], v225 offset:32768
	ds_read_b128 v[54:57], v225 offset:33792
	ds_read_b128 v[238:241], v225 offset:34816
	ds_read_b128 v[242:245], v225 offset:35840
	ds_read_b128 v[246:249], v225 offset:36864
	ds_read_b128 v[214:217], v225 offset:37888
	ds_read_b128 v[168:171], v225 offset:38912
	ds_read_b128 v[172:175], v225 offset:39936
	global_load_lds_dwordx4 v[58:59], off
	v_lshl_add_u64 v[58:59], s[26:27], 0, v[154:155]
	s_mov_b32 m0, s40
	s_nop 0
	global_load_lds_dwordx4 v[58:59], off
	s_waitcnt vmcnt(8)
	s_waitcnt lgkmcnt(0)
	s_barrier
	s_setprio 1
	s_waitcnt lgkmcnt(0)
	v_mfma_f32_16x16x32_bf16 v[58:61], v[18:21], v[50:53], v[66:69]
	v_mfma_f32_16x16x32_bf16 v[146:149], v[22:25], v[54:57], v[58:61]
	v_mfma_f32_16x16x32_bf16 v[58:61], v[26:29], v[50:53], v[70:73]
	v_mfma_f32_16x16x32_bf16 v[150:153], v[30:33], v[54:57], v[58:61]
	v_mfma_f32_16x16x32_bf16 v[58:61], v[18:21], v[238:241], v[74:77]
	v_mfma_f32_16x16x32_bf16 v[126:129], v[22:25], v[242:245], v[58:61]
	v_mfma_f32_16x16x32_bf16 v[58:61], v[26:29], v[238:241], v[78:81]
	v_mfma_f32_16x16x32_bf16 v[122:125], v[30:33], v[242:245], v[58:61]
	v_mfma_f32_16x16x32_bf16 v[58:61], v[18:21], v[246:249], v[82:85]
	v_mfma_f32_16x16x32_bf16 v[118:121], v[22:25], v[214:217], v[58:61]
	v_mfma_f32_16x16x32_bf16 v[58:61], v[26:29], v[246:249], v[86:89]
	v_mfma_f32_16x16x32_bf16 v[114:117], v[30:33], v[214:217], v[58:61]
	v_mfma_f32_16x16x32_bf16 v[58:61], v[18:21], v[168:171], v[90:93]
	v_mfma_f32_16x16x32_bf16 v[102:105], v[22:25], v[172:175], v[58:61]
	v_mfma_f32_16x16x32_bf16 v[58:61], v[26:29], v[168:171], v[94:97]
	v_mfma_f32_16x16x32_bf16 v[98:101], v[30:33], v[172:175], v[58:61]
	s_setprio 0
	s_setprio 1
	v_mfma_f32_16x16x32_bf16 v[58:61], v[160:163], v[50:53], v[210:213]
	v_mfma_f32_16x16x32_bf16 v[34:37], v[202:205], v[50:53], v[34:37]
	v_mfma_f32_16x16x32_bf16 v[62:65], v[198:201], v[54:57], v[58:61]
	v_mfma_f32_16x16x32_bf16 v[58:61], v[234:237], v[54:57], v[34:37]
	v_mfma_f32_16x16x32_bf16 v[34:37], v[160:163], v[238:241], v[38:41]
	v_mfma_f32_16x16x32_bf16 v[54:57], v[198:201], v[242:245], v[34:37]
	v_mfma_f32_16x16x32_bf16 v[34:37], v[202:205], v[238:241], v[42:45]
	v_mfma_f32_16x16x32_bf16 v[50:53], v[234:237], v[242:245], v[34:37]
	v_mfma_f32_16x16x32_bf16 v[34:37], v[160:163], v[246:249], v[46:49]
	v_mfma_f32_16x16x32_bf16 v[46:49], v[198:201], v[214:217], v[34:37]
	v_mfma_f32_16x16x32_bf16 v[34:37], v[202:205], v[246:249], v[178:181]
	v_mfma_f32_16x16x32_bf16 v[42:45], v[234:237], v[214:217], v[34:37]
	v_mfma_f32_16x16x32_bf16 v[34:37], v[160:163], v[168:171], v[182:185]
	v_mfma_f32_16x16x32_bf16 v[38:41], v[198:201], v[172:175], v[34:37]
	v_mfma_f32_16x16x32_bf16 v[34:37], v[202:205], v[168:171], v[186:189]
	v_mfma_f32_16x16x32_bf16 v[34:37], v[234:237], v[172:175], v[34:37]
	s_setprio 0
	s_barrier
	s_mov_b32 m0, s17
	v_lshl_add_u64 v[66:67], v[164:165], 0, s[42:43]
	s_add_u32 s4, s4, 0x10080
	ds_read_b128 v[168:171], v225 offset:49152
	ds_read_b128 v[172:175], v225 offset:50176
	ds_read_b128 v[178:181], v225 offset:51200
	ds_read_b128 v[182:185], v225 offset:52224
	ds_read_b128 v[186:189], v225 offset:53248
	ds_read_b128 v[210:213], v225 offset:54272
	ds_read_b128 v[214:217], v225 offset:55296
	ds_read_b128 v[238:241], v225 offset:56320
	global_load_lds_dwordx4 v[66:67], off
	v_lshl_add_u64 v[66:67], v[250:251], 0, s[42:43]
	s_mov_b32 m0, vcc_hi
	s_addc_u32 s5, s5, 0
	global_load_lds_dwordx4 v[66:67], off
	v_lshl_add_u64 v[66:67], s[4:5], 0, v[12:13]
	s_mov_b32 m0, s6
	s_nop 0
	global_load_lds_dwordx4 v[66:67], off
	v_lshl_add_u64 v[66:67], s[4:5], 0, v[154:155]
	s_mov_b32 m0, s7
	s_nop 0
	global_load_lds_dwordx4 v[66:67], off
	v_lshl_add_u64 v[66:67], v[218:219], 0, s[42:43]
	s_mov_b32 m0, s63
	s_nop 0
	global_load_lds_dwordx4 v[66:67], off
	v_lshl_add_u64 v[66:67], v[176:177], 0, s[42:43]
	s_mov_b32 m0, s64
	s_nop 0
	global_load_lds_dwordx4 v[66:67], off
	s_waitcnt vmcnt(8)
	s_waitcnt lgkmcnt(0)
	s_barrier
	s_setprio 1
	s_waitcnt lgkmcnt(0)
	v_mfma_f32_16x16x32_bf16 v[66:69], v[18:21], v[168:171], v[130:133]
	v_mfma_f32_16x16x32_bf16 v[94:97], v[22:25], v[172:175], v[66:69]
	v_mfma_f32_16x16x32_bf16 v[66:69], v[26:29], v[168:171], v[134:137]
	v_mfma_f32_16x16x32_bf16 v[90:93], v[30:33], v[172:175], v[66:69]
	v_mfma_f32_16x16x32_bf16 v[66:69], v[18:21], v[178:181], v[138:141]
	v_mfma_f32_16x16x32_bf16 v[86:89], v[22:25], v[182:185], v[66:69]
	v_mfma_f32_16x16x32_bf16 v[66:69], v[26:29], v[178:181], v[142:145]
	v_mfma_f32_16x16x32_bf16 v[82:85], v[30:33], v[182:185], v[66:69]
	v_mfma_f32_16x16x32_bf16 v[66:69], v[18:21], v[186:189], v[206:209]
	v_mfma_f32_16x16x32_bf16 v[0:3], v[18:21], v[214:217], v[0:3]
	v_mfma_f32_16x16x32_bf16 v[78:81], v[22:25], v[210:213], v[66:69]
	v_mfma_f32_16x16x32_bf16 v[66:69], v[26:29], v[186:189], v[226:229]
	v_mfma_f32_16x16x32_bf16 v[70:73], v[22:25], v[238:241], v[0:3]
	v_mfma_f32_16x16x32_bf16 v[0:3], v[26:29], v[214:217], v[4:7]
	v_mfma_f32_16x16x32_bf16 v[74:77], v[30:33], v[210:213], v[66:69]
	v_mfma_f32_16x16x32_bf16 v[66:69], v[30:33], v[238:241], v[0:3]
	s_setprio 0
	s_setprio 1
	v_mfma_f32_16x16x32_bf16 v[0:3], v[160:163], v[168:171], v[8:11]
	v_mfma_f32_16x16x32_bf16 v[30:33], v[198:201], v[172:175], v[0:3]
	v_mfma_f32_16x16x32_bf16 v[0:3], v[202:205], v[168:171], v[14:17]
	v_mfma_f32_16x16x32_bf16 v[26:29], v[234:237], v[172:175], v[0:3]
	v_mfma_f32_16x16x32_bf16 v[0:3], v[160:163], v[178:181], v[106:109]
	v_mfma_f32_16x16x32_bf16 v[22:25], v[198:201], v[182:185], v[0:3]
	v_mfma_f32_16x16x32_bf16 v[0:3], v[202:205], v[178:181], v[110:113]
	v_mfma_f32_16x16x32_bf16 v[18:21], v[234:237], v[182:185], v[0:3]
	v_mfma_f32_16x16x32_bf16 v[0:3], v[160:163], v[186:189], v[230:233]
	v_mfma_f32_16x16x32_bf16 v[14:17], v[198:201], v[210:213], v[0:3]
	v_mfma_f32_16x16x32_bf16 v[0:3], v[202:205], v[186:189], v[190:193]
	v_mfma_f32_16x16x32_bf16 v[8:11], v[234:237], v[210:213], v[0:3]
	v_mfma_f32_16x16x32_bf16 v[0:3], v[160:163], v[214:217], v[194:197]
	v_mfma_f32_16x16x32_bf16 v[4:7], v[198:201], v[238:241], v[0:3]
	v_mfma_f32_16x16x32_bf16 v[0:3], v[202:205], v[214:217], v[156:159]
	v_mfma_f32_16x16x32_bf16 v[0:3], v[234:237], v[238:241], v[0:3]
	s_setprio 0
	s_barrier
	s_andn2_b64 vcc, exec, s[10:11]
	s_cbranch_vccnz .LBB0_522
	s_barrier

.Lf3_nockp:
	s_mov_b32 m0, s55
	s_or_b64 exec, exec, s[12:13]
	global_load_lds_dwordx4 v[248:249], off
	s_mov_b64 s[14:15], 0x10000
	v_lshl_add_u64 v[242:243], v[244:245], 0, s[14:15]
	v_lshl_add_u64 v[244:245], v[242:243], 0, s[14:15]
	v_lshl_add_u64 v[246:247], v[248:249], 0, s[14:15]
	v_lshl_add_u64 v[248:249], v[246:247], 0, s[14:15]
	s_mov_b64 s[14:15], 0x100
	v_lshl_add_u64 v[250:251], v[250:251], 0, s[14:15]
	ds_read_b128 v[78:81], v158 offset:43264
	ds_read_b128 v[82:85], v158 offset:43296
	ds_read_b128 v[86:89], v158 offset:43328
	ds_read_b128 v[90:93], v158 offset:43360
	ds_read_b128 v[94:97], v158 offset:43392
	ds_read_b128 v[98:101], v158 offset:43424
	ds_read_b128 v[102:105], v158 offset:43456
	ds_read_b128 v[106:109], v158 offset:43488
	s_waitcnt lgkmcnt(4)
	ds_read_b128 v[190:193], v218 offset:13312
	ds_read_b128 v[194:197], v218 offset:17920
	ds_read_b128 v[198:201], v218 offset:13344
	ds_read_b128 v[202:205], v218 offset:17952
	ds_read_b128 v[206:209], v218 offset:13376
	ds_read_b128 v[210:213], v218 offset:17984
	ds_read_b128 v[214:217], v218 offset:13408
	ds_read_b128 v[222:225], v218 offset:18016
	v_max3_f32 v124, v46, v47, v48
	v_max3_f32 v125, v49, v50, v51
	v_max3_f32 v124, v124, v52, v53
	v_max3_f32 v125, v125, v54, v55
	v_max3_f32 v124, v124, v56, v57
	v_max3_f32 v125, v125, v58, v59
	v_max3_f32 v124, v124, v60, v61
	v_max3_f32 v125, v125, v62, v63
	v_max3_f32 v124, v124, v64, v65
	v_max3_f32 v125, v125, v66, v67
	v_max3_f32 v124, v124, v68, v69
	v_max3_f32 v125, v125, v70, v71
	v_max3_f32 v124, v124, v72, v73
	v_max3_f32 v125, v125, v74, v75
	v_max3_f32 v124, v124, v76, v77
	v_max_f32_e32 v124, v124, v125
	v_mov_b32_e32 v125, v124
	s_nop 1
	v_permlane32_swap_b32_e32 v124, v125
	v_max_f32_e32 v126, v124, v125
	s_add_i32 s12, s10, 6
	s_cmp_lt_i32 s12, s41
	s_cbranch_scc1 .Lf3_loop
	s_add_i32 s12, s10, 4
	s_cmp_lt_i32 s12, s41
	s_cbranch_scc1 .Lf3_tail0
	s_branch .Lf3_tail2

.Lf3_nocka:
	s_mov_b32 m0, s54
	s_or_b64 exec, exec, s[12:13]
	global_load_lds_dwordx4 v[246:247], off
	v_max3_f32 v125, v125, v86, v87
	v_max3_f32 v124, v124, v88, v89
	v_max3_f32 v125, v125, v90, v91
	v_mfma_f32_32x32x16_bf16 v[14:29], v[198:201], v[230:233], v[14:29]
	ds_read_b128 v[198:201], v218 offset:32
	v_max3_f32 v124, v124, v92, v93
	v_max3_f32 v125, v125, v94, v95
	v_max3_f32 v124, v124, v96, v97
	v_mfma_f32_32x32x16_bf16 v[30:45], v[202:205], v[230:233], v[30:45]
	ds_read_b128 v[202:205], v218 offset:4640
	v_max3_f32 v125, v125, v98, v99
	v_max3_f32 v124, v124, v100, v101
	v_max3_f32 v125, v125, v102, v103
	v_mfma_f32_32x32x16_bf16 v[14:29], v[206:209], v[234:237], v[14:29]
	ds_read_b128 v[206:209], v218 offset:64
	v_max3_f32 v124, v124, v104, v105
	v_max3_f32 v125, v125, v106, v107
	v_mfma_f32_32x32x16_bf16 v[30:45], v[210:213], v[234:237], v[30:45]
	ds_read_b128 v[210:213], v218 offset:4672
	v_max3_f32 v124, v124, v108, v109
	v_max_f32_e32 v124, v124, v125
	v_mfma_f32_32x32x16_bf16 v[14:29], v[214:217], v[238:241], v[14:29]
	ds_read_b128 v[214:217], v218 offset:96
	v_mov_b32_e32 v125, v124
	s_nop 1
	v_mfma_f32_32x32x16_bf16 v[30:45], v[222:225], v[238:241], v[30:45]
	s_waitcnt lgkmcnt(14)
	ds_read_b128 v[222:225], v218 offset:4704
	v_permlane32_swap_b32_e32 v124, v125
	v_max_f32_e32 v126, v124, v125
	v_lshl_add_u64 v[242:243], v[242:243], 0, s[46:47]
	v_lshl_add_u64 v[246:247], v[246:247], 0, s[46:47]
	v_add_f32_e32 v127, 0x41800000, v160
	v_cmp_gt_f32_e32 vcc, v126, v127
	s_cbranch_vccnz .Lf3_rescb

.Lf3_nockb:
	s_mov_b32 m0, s55
	s_or_b64 exec, exec, s[12:13]
	global_load_lds_dwordx4 v[248:249], off
	v_max3_f32 v125, v125, v54, v55
	v_max3_f32 v124, v124, v56, v57
	v_max3_f32 v125, v125, v58, v59
	v_mfma_f32_32x32x16_bf16 v[14:29], v[198:201], v[230:233], v[14:29]
	ds_read_b128 v[198:201], v218 offset:13344
	v_max3_f32 v124, v124, v60, v61
	v_max3_f32 v125, v125, v62, v63
	v_max3_f32 v124, v124, v64, v65
	v_mfma_f32_32x32x16_bf16 v[30:45], v[202:205], v[230:233], v[30:45]
	ds_read_b128 v[202:205], v218 offset:17952
	v_max3_f32 v125, v125, v66, v67
	v_max3_f32 v124, v124, v68, v69
	v_max3_f32 v125, v125, v70, v71
	v_mfma_f32_32x32x16_bf16 v[14:29], v[206:209], v[234:237], v[14:29]
	ds_read_b128 v[206:209], v218 offset:13376
	v_max3_f32 v124, v124, v72, v73
	v_max3_f32 v125, v125, v74, v75
	v_mfma_f32_32x32x16_bf16 v[30:45], v[210:213], v[234:237], v[30:45]
	ds_read_b128 v[210:213], v218 offset:17984
	v_max3_f32 v124, v124, v76, v77
	v_max_f32_e32 v124, v124, v125
	v_mfma_f32_32x32x16_bf16 v[14:29], v[214:217], v[238:241], v[14:29]
	ds_read_b128 v[214:217], v218 offset:13408
	v_mov_b32_e32 v125, v124
	s_nop 1
	v_mfma_f32_32x32x16_bf16 v[30:45], v[222:225], v[238:241], v[30:45]
	s_waitcnt lgkmcnt(14)
	ds_read_b128 v[222:225], v218 offset:18016
	v_permlane32_swap_b32_e32 v124, v125
	v_max_f32_e32 v126, v124, v125
	v_lshl_add_u64 v[244:245], v[244:245], 0, s[46:47]
	v_lshl_add_u64 v[248:249], v[248:249], 0, s[46:47]
	v_lshl_add_u64 v[250:251], v[250:251], 0, s[48:49]
	s_add_i32 s10, s10, 2
	s_add_i32 s12, s10, 6
	s_cmp_lt_i32 s12, s41
	s_cbranch_scc1 .Lf3_loop

.Lf3_nockt0FULL:
	s_mov_b32 m0, s54
	s_or_b64 exec, exec, s[12:13]
	global_load_lds_dwordx4 v[246:247], off
	v_max3_f32 v125, v125, v86, v87
	v_max3_f32 v124, v124, v88, v89
	v_max3_f32 v125, v125, v90, v91
	v_mfma_f32_32x32x16_bf16 v[14:29], v[198:201], v[230:233], v[14:29]
	ds_read_b128 v[198:201], v218 offset:32
	v_max3_f32 v124, v124, v92, v93
	v_max3_f32 v125, v125, v94, v95
	v_max3_f32 v124, v124, v96, v97
	v_mfma_f32_32x32x16_bf16 v[30:45], v[202:205], v[230:233], v[30:45]
	ds_read_b128 v[202:205], v218 offset:4640
	v_max3_f32 v125, v125, v98, v99
	v_max3_f32 v124, v124, v100, v101
	v_max3_f32 v125, v125, v102, v103
	v_mfma_f32_32x32x16_bf16 v[14:29], v[206:209], v[234:237], v[14:29]
	ds_read_b128 v[206:209], v218 offset:64
	v_max3_f32 v124, v124, v104, v105
	v_max3_f32 v125, v125, v106, v107
	v_mfma_f32_32x32x16_bf16 v[30:45], v[210:213], v[234:237], v[30:45]
	ds_read_b128 v[210:213], v218 offset:4672
	v_max3_f32 v124, v124, v108, v109
	v_max_f32_e32 v124, v124, v125
	v_mfma_f32_32x32x16_bf16 v[14:29], v[214:217], v[238:241], v[14:29]
	ds_read_b128 v[214:217], v218 offset:96
	v_mov_b32_e32 v125, v124
	s_nop 1
	v_mfma_f32_32x32x16_bf16 v[30:45], v[222:225], v[238:241], v[30:45]
	s_waitcnt lgkmcnt(14)
	ds_read_b128 v[222:225], v218 offset:4704
	v_permlane32_swap_b32_e32 v124, v125
	v_max_f32_e32 v126, v124, v125
	v_lshl_add_u64 v[242:243], v[242:243], 0, s[46:47]
	v_lshl_add_u64 v[246:247], v[246:247], 0, s[46:47]

.Lf3_nockt1FULLM:
	s_mov_b32 m0, s55
	s_or_b64 exec, exec, s[12:13]
	global_load_lds_dwordx4 v[248:249], off
	v_cndmask_b32_e64 v48, v220, v48, s[14:15]
	v_cmp_le_i32_e64 s[14:15], 35, v219
	v_cndmask_b32_e64 v64, v220, v64, s[16:17]
	v_cmp_le_i32_e64 s[16:17], 8, v219
	v_cndmask_b32_e64 v49, v220, v49, s[52:53]
	v_cmp_le_i32_e64 s[52:53], 40, v219
	v_cndmask_b32_e64 v65, v220, v65, s[14:15]
	v_cmp_le_i32_e64 s[14:15], 9, v219
	v_cndmask_b32_e64 v50, v220, v50, s[16:17]
	v_cmp_le_i32_e64 s[16:17], 41, v219
	v_cndmask_b32_e64 v66, v220, v66, s[52:53]
	v_mfma_f32_32x32x16_bf16 v[14:29], v[198:201], v[230:233], v[14:29]
	ds_read_b128 v[198:201], v218 offset:13344
	v_cmp_le_i32_e64 s[52:53], 10, v219
	v_cndmask_b32_e64 v51, v220, v51, s[14:15]
	v_cmp_le_i32_e64 s[14:15], 42, v219
	v_cndmask_b32_e64 v67, v220, v67, s[16:17]
	v_cmp_le_i32_e64 s[16:17], 11, v219
	v_cndmask_b32_e64 v52, v220, v52, s[52:53]
	v_cmp_le_i32_e64 s[52:53], 43, v219
	v_cndmask_b32_e64 v68, v220, v68, s[14:15]
	v_cmp_le_i32_e64 s[14:15], 16, v219
	v_cndmask_b32_e64 v53, v220, v53, s[16:17]
	v_cmp_le_i32_e64 s[16:17], 48, v219
	v_mfma_f32_32x32x16_bf16 v[30:45], v[202:205], v[230:233], v[30:45]
	ds_read_b128 v[202:205], v218 offset:17952
	v_cndmask_b32_e64 v69, v220, v69, s[52:53]
	v_cmp_le_i32_e64 s[52:53], 17, v219
	v_cndmask_b32_e64 v54, v220, v54, s[14:15]
	v_cmp_le_i32_e64 s[14:15], 49, v219
	v_cndmask_b32_e64 v70, v220, v70, s[16:17]
	v_cmp_le_i32_e64 s[16:17], 18, v219
	v_cndmask_b32_e64 v55, v220, v55, s[52:53]
	v_cmp_le_i32_e64 s[52:53], 50, v219
	v_cndmask_b32_e64 v71, v220, v71, s[14:15]
	v_cmp_le_i32_e64 s[14:15], 19, v219
	v_cndmask_b32_e64 v56, v220, v56, s[16:17]
	v_mfma_f32_32x32x16_bf16 v[14:29], v[206:209], v[234:237], v[14:29]
	ds_read_b128 v[206:209], v218 offset:13376
	v_cmp_le_i32_e64 s[16:17], 51, v219
	v_cndmask_b32_e64 v72, v220, v72, s[52:53]
	v_cmp_le_i32_e64 s[52:53], 24, v219
	v_cndmask_b32_e64 v57, v220, v57, s[14:15]
	v_cmp_le_i32_e64 s[14:15], 56, v219
	v_cndmask_b32_e64 v73, v220, v73, s[16:17]
	v_cmp_le_i32_e64 s[16:17], 25, v219
	v_cndmask_b32_e64 v58, v220, v58, s[52:53]
	v_cmp_le_i32_e64 s[52:53], 57, v219
	v_cndmask_b32_e64 v74, v220, v74, s[14:15]
	v_mfma_f32_32x32x16_bf16 v[30:45], v[210:213], v[234:237], v[30:45]
	ds_read_b128 v[210:213], v218 offset:17984
	v_cmp_le_i32_e64 s[14:15], 26, v219
	v_cndmask_b32_e64 v59, v220, v59, s[16:17]
	v_cmp_le_i32_e64 s[16:17], 58, v219
	v_cndmask_b32_e64 v75, v220, v75, s[52:53]
	v_cmp_le_i32_e64 s[52:53], 27, v219
	v_cndmask_b32_e64 v60, v220, v60, s[14:15]
	v_cmp_le_i32_e64 s[14:15], 59, v219
	v_cndmask_b32_e64 v76, v220, v76, s[16:17]
	v_cndmask_b32_e64 v61, v220, v61, s[52:53]
	v_cndmask_b32_e64 v77, v220, v77, s[14:15]
	v_mfma_f32_32x32x16_bf16 v[14:29], v[214:217], v[238:241], v[14:29]
	ds_read_b128 v[214:217], v218 offset:13408
	v_max3_f32 v124, v46, v47, v48
	v_max3_f32 v125, v49, v50, v51
	v_max3_f32 v124, v124, v52, v53
	v_max3_f32 v125, v125, v54, v55
	v_max3_f32 v124, v124, v56, v57
	v_max3_f32 v125, v125, v58, v59
	v_max3_f32 v124, v124, v60, v61
	v_max3_f32 v125, v125, v62, v63
	v_max3_f32 v124, v124, v64, v65
	v_max3_f32 v125, v125, v66, v67
	v_mfma_f32_32x32x16_bf16 v[30:45], v[222:225], v[238:241], v[30:45]
	s_waitcnt lgkmcnt(14)
	ds_read_b128 v[222:225], v218 offset:18016
	v_max3_f32 v124, v124, v68, v69
	v_max3_f32 v125, v125, v70, v71
	v_max3_f32 v124, v124, v72, v73
	v_max3_f32 v125, v125, v74, v75
	v_max3_f32 v124, v124, v76, v77
	v_max_f32_e32 v124, v124, v125
	v_mov_b32_e32 v125, v124
	s_nop 1
	v_permlane32_swap_b32_e32 v124, v125
	v_max_f32_e32 v126, v124, v125
	v_lshl_add_u64 v[244:245], v[244:245], 0, s[46:47]
	v_lshl_add_u64 v[248:249], v[248:249], 0, s[46:47]
	v_lshl_add_u64 v[250:251], v[250:251], 0, s[48:49]
	s_branch .Lf3_tail2

.Lf3_nockt1FULL:
	s_mov_b32 m0, s55
	s_or_b64 exec, exec, s[12:13]
	global_load_lds_dwordx4 v[248:249], off
	v_max3_f32 v125, v125, v54, v55
	v_max3_f32 v124, v124, v56, v57
	v_max3_f32 v125, v125, v58, v59
	v_mfma_f32_32x32x16_bf16 v[14:29], v[198:201], v[230:233], v[14:29]
	ds_read_b128 v[198:201], v218 offset:13344
	v_max3_f32 v124, v124, v60, v61
	v_max3_f32 v125, v125, v62, v63
	v_max3_f32 v124, v124, v64, v65
	v_mfma_f32_32x32x16_bf16 v[30:45], v[202:205], v[230:233], v[30:45]
	ds_read_b128 v[202:205], v218 offset:17952
	v_max3_f32 v125, v125, v66, v67
	v_max3_f32 v124, v124, v68, v69
	v_max3_f32 v125, v125, v70, v71
	v_mfma_f32_32x32x16_bf16 v[14:29], v[206:209], v[234:237], v[14:29]
	ds_read_b128 v[206:209], v218 offset:13376
	v_max3_f32 v124, v124, v72, v73
	v_max3_f32 v125, v125, v74, v75
	v_mfma_f32_32x32x16_bf16 v[30:45], v[210:213], v[234:237], v[30:45]
	ds_read_b128 v[210:213], v218 offset:17984
	v_max3_f32 v124, v124, v76, v77
	v_max_f32_e32 v124, v124, v125
	v_mfma_f32_32x32x16_bf16 v[14:29], v[214:217], v[238:241], v[14:29]
	ds_read_b128 v[214:217], v218 offset:13408
	v_mov_b32_e32 v125, v124
	s_nop 1
	v_mfma_f32_32x32x16_bf16 v[30:45], v[222:225], v[238:241], v[30:45]
	s_waitcnt lgkmcnt(14)
	ds_read_b128 v[222:225], v218 offset:18016
	v_permlane32_swap_b32_e32 v124, v125
	v_max_f32_e32 v126, v124, v125
	v_lshl_add_u64 v[244:245], v[244:245], 0, s[46:47]
	v_lshl_add_u64 v[248:249], v[248:249], 0, s[46:47]
	v_lshl_add_u64 v[250:251], v[250:251], 0, s[48:49]

.Lf3_nockt2CONLY:
	s_mov_b32 m0, s54
	s_or_b64 exec, exec, s[12:13]
	global_load_lds_dwordx4 v[246:247], off
	v_mfma_f32_32x32x16_bf16 v[14:29], v[198:201], v[230:233], v[14:29]
	v_mfma_f32_32x32x16_bf16 v[30:45], v[202:205], v[230:233], v[30:45]
	v_mfma_f32_32x32x16_bf16 v[14:29], v[206:209], v[234:237], v[14:29]
	v_mfma_f32_32x32x16_bf16 v[30:45], v[210:213], v[234:237], v[30:45]
	v_mfma_f32_32x32x16_bf16 v[14:29], v[214:217], v[238:241], v[14:29]
	v_mfma_f32_32x32x16_bf16 v[30:45], v[222:225], v[238:241], v[30:45]
	v_lshl_add_u64 v[242:243], v[242:243], 0, s[46:47]
	v_lshl_add_u64 v[246:247], v[246:247], 0, s[46:47]
	s_branch .Lf3_tail3

.Lf3_nockt2FULL:
	s_mov_b32 m0, s54
	s_or_b64 exec, exec, s[12:13]
	global_load_lds_dwordx4 v[246:247], off
	v_max3_f32 v125, v125, v86, v87
	v_max3_f32 v124, v124, v88, v89
	v_max3_f32 v125, v125, v90, v91
	v_mfma_f32_32x32x16_bf16 v[14:29], v[198:201], v[230:233], v[14:29]
	ds_read_b128 v[198:201], v218 offset:32
	v_max3_f32 v124, v124, v92, v93
	v_max3_f32 v125, v125, v94, v95
	v_max3_f32 v124, v124, v96, v97
	v_mfma_f32_32x32x16_bf16 v[30:45], v[202:205], v[230:233], v[30:45]
	ds_read_b128 v[202:205], v218 offset:4640
	v_max3_f32 v125, v125, v98, v99
	v_max3_f32 v124, v124, v100, v101
	v_max3_f32 v125, v125, v102, v103
	v_mfma_f32_32x32x16_bf16 v[14:29], v[206:209], v[234:237], v[14:29]
	ds_read_b128 v[206:209], v218 offset:64
	v_max3_f32 v124, v124, v104, v105
	v_max3_f32 v125, v125, v106, v107
	v_mfma_f32_32x32x16_bf16 v[30:45], v[210:213], v[234:237], v[30:45]
	ds_read_b128 v[210:213], v218 offset:4672
	v_max3_f32 v124, v124, v108, v109
	v_max_f32_e32 v124, v124, v125
	v_mfma_f32_32x32x16_bf16 v[14:29], v[214:217], v[238:241], v[14:29]
	ds_read_b128 v[214:217], v218 offset:96
	v_mov_b32_e32 v125, v124
	s_nop 1
	v_mfma_f32_32x32x16_bf16 v[30:45], v[222:225], v[238:241], v[30:45]
	s_waitcnt lgkmcnt(14)
	ds_read_b128 v[222:225], v218 offset:4704
	v_permlane32_swap_b32_e32 v124, v125
	v_max_f32_e32 v126, v124, v125
	v_lshl_add_u64 v[242:243], v[242:243], 0, s[46:47]
	v_lshl_add_u64 v[246:247], v[246:247], 0, s[46:47]
	s_branch .Lf3_tail3

.Lf3_nockt2FULLM:
	s_mov_b32 m0, s54
	s_or_b64 exec, exec, s[12:13]
	global_load_lds_dwordx4 v[246:247], off
	v_cndmask_b32_e64 v80, v220, v80, s[14:15]
	v_cmp_le_i32_e64 s[14:15], 35, v219
	v_cndmask_b32_e64 v96, v220, v96, s[16:17]
	v_cmp_le_i32_e64 s[16:17], 8, v219
	v_cndmask_b32_e64 v81, v220, v81, s[52:53]
	v_cmp_le_i32_e64 s[52:53], 40, v219
	v_cndmask_b32_e64 v97, v220, v97, s[14:15]
	v_cmp_le_i32_e64 s[14:15], 9, v219
	v_cndmask_b32_e64 v82, v220, v82, s[16:17]
	v_cmp_le_i32_e64 s[16:17], 41, v219
	v_cndmask_b32_e64 v98, v220, v98, s[52:53]
	v_mfma_f32_32x32x16_bf16 v[14:29], v[198:201], v[230:233], v[14:29]
	ds_read_b128 v[198:201], v218 offset:32
	v_cmp_le_i32_e64 s[52:53], 10, v219
	v_cndmask_b32_e64 v83, v220, v83, s[14:15]
	v_cmp_le_i32_e64 s[14:15], 42, v219
	v_cndmask_b32_e64 v99, v220, v99, s[16:17]
	v_cmp_le_i32_e64 s[16:17], 11, v219
	v_cndmask_b32_e64 v84, v220, v84, s[52:53]
	v_cmp_le_i32_e64 s[52:53], 43, v219
	v_cndmask_b32_e64 v100, v220, v100, s[14:15]
	v_cmp_le_i32_e64 s[14:15], 16, v219
	v_cndmask_b32_e64 v85, v220, v85, s[16:17]
	v_cmp_le_i32_e64 s[16:17], 48, v219
	v_mfma_f32_32x32x16_bf16 v[30:45], v[202:205], v[230:233], v[30:45]
	ds_read_b128 v[202:205], v218 offset:4640
	v_cndmask_b32_e64 v101, v220, v101, s[52:53]
	v_cmp_le_i32_e64 s[52:53], 17, v219
	v_cndmask_b32_e64 v86, v220, v86, s[14:15]
	v_cmp_le_i32_e64 s[14:15], 49, v219
	v_cndmask_b32_e64 v102, v220, v102, s[16:17]
	v_cmp_le_i32_e64 s[16:17], 18, v219
	v_cndmask_b32_e64 v87, v220, v87, s[52:53]
	v_cmp_le_i32_e64 s[52:53], 50, v219
	v_cndmask_b32_e64 v103, v220, v103, s[14:15]
	v_cmp_le_i32_e64 s[14:15], 19, v219
	v_cndmask_b32_e64 v88, v220, v88, s[16:17]
	v_mfma_f32_32x32x16_bf16 v[14:29], v[206:209], v[234:237], v[14:29]
	ds_read_b128 v[206:209], v218 offset:64
	v_cmp_le_i32_e64 s[16:17], 51, v219
	v_cndmask_b32_e64 v104, v220, v104, s[52:53]
	v_cmp_le_i32_e64 s[52:53], 24, v219
	v_cndmask_b32_e64 v89, v220, v89, s[14:15]
	v_cmp_le_i32_e64 s[14:15], 56, v219
	v_cndmask_b32_e64 v105, v220, v105, s[16:17]
	v_cmp_le_i32_e64 s[16:17], 25, v219
	v_cndmask_b32_e64 v90, v220, v90, s[52:53]
	v_cmp_le_i32_e64 s[52:53], 57, v219
	v_cndmask_b32_e64 v106, v220, v106, s[14:15]
	v_mfma_f32_32x32x16_bf16 v[30:45], v[210:213], v[234:237], v[30:45]
	ds_read_b128 v[210:213], v218 offset:4672
	v_cmp_le_i32_e64 s[14:15], 26, v219
	v_cndmask_b32_e64 v91, v220, v91, s[16:17]
	v_cmp_le_i32_e64 s[16:17], 58, v219
	v_cndmask_b32_e64 v107, v220, v107, s[52:53]
	v_cmp_le_i32_e64 s[52:53], 27, v219
	v_cndmask_b32_e64 v92, v220, v92, s[14:15]
	v_cmp_le_i32_e64 s[14:15], 59, v219
	v_cndmask_b32_e64 v108, v220, v108, s[16:17]
	v_cndmask_b32_e64 v93, v220, v93, s[52:53]
	v_cndmask_b32_e64 v109, v220, v109, s[14:15]
	v_mfma_f32_32x32x16_bf16 v[14:29], v[214:217], v[238:241], v[14:29]
	ds_read_b128 v[214:217], v218 offset:96
	v_max3_f32 v124, v78, v79, v80
	v_max3_f32 v125, v81, v82, v83
	v_max3_f32 v124, v124, v84, v85
	v_max3_f32 v125, v125, v86, v87
	v_max3_f32 v124, v124, v88, v89
	v_max3_f32 v125, v125, v90, v91
	v_max3_f32 v124, v124, v92, v93
	v_max3_f32 v125, v125, v94, v95
	v_max3_f32 v124, v124, v96, v97
	v_max3_f32 v125, v125, v98, v99
	v_mfma_f32_32x32x16_bf16 v[30:45], v[222:225], v[238:241], v[30:45]
	s_waitcnt lgkmcnt(14)
	ds_read_b128 v[222:225], v218 offset:4704
	v_max3_f32 v124, v124, v100, v101
	v_max3_f32 v125, v125, v102, v103
	v_max3_f32 v124, v124, v104, v105
	v_max3_f32 v125, v125, v106, v107
	v_max3_f32 v124, v124, v108, v109
	v_max_f32_e32 v124, v124, v125
	v_mov_b32_e32 v125, v124
	s_nop 1
	v_permlane32_swap_b32_e32 v124, v125
	v_max_f32_e32 v126, v124, v125
	v_lshl_add_u64 v[242:243], v[242:243], 0, s[46:47]
	v_lshl_add_u64 v[246:247], v[246:247], 0, s[46:47]

.Lf3_nocwt3FULL:
	s_or_b64 exec, exec, s[12:13]
	v_exp_f32_e32 v102, v102
	v_exp_f32_e32 v103, v103
	v_exp_f32_e32 v104, v104
	v_exp_f32_e32 v105, v105
	v_exp_f32_e32 v106, v106
	v_exp_f32_e32 v107, v107
	v_exp_f32_e32 v108, v108
	v_exp_f32_e32 v109, v109
	v_add_f32_e32 v122, v122, v102
	v_add_f32_e32 v123, v123, v103
	v_add_f32_e32 v122, v122, v104
	v_add_f32_e32 v123, v123, v105
	v_add_f32_e32 v122, v122, v106
	v_add_f32_e32 v123, v123, v107
	v_add_f32_e32 v122, v122, v108
	v_add_f32_e32 v123, v123, v109
	v_cvt_pk_bf16_f32 v238, v102, v103
	v_cvt_pk_bf16_f32 v239, v104, v105
	v_cvt_pk_bf16_f32 v240, v106, v107
	v_cvt_pk_bf16_f32 v241, v108, v109
	v_add_f32_e32 v122, v122, v123
	v_add_f32_e32 v161, v161, v122
	s_waitcnt lgkmcnt(0)
	s_barrier
	ds_read_b128 v[78:81], v158 offset:43264
	ds_read_b128 v[82:85], v158 offset:43296
	ds_read_b128 v[86:89], v158 offset:43328
	ds_read_b128 v[90:93], v158 offset:43360
	ds_read_b128 v[94:97], v158 offset:43392
	ds_read_b128 v[98:101], v158 offset:43424
	ds_read_b128 v[102:105], v158 offset:43456
	ds_read_b128 v[106:109], v158 offset:43488
	v_mfma_f32_32x32x16_bf16 v[14:29], v[190:193], v[226:229], v[14:29]
	ds_read_b128 v[190:193], v218 offset:13312
	v_max3_f32 v124, v46, v47, v48
	v_max3_f32 v125, v49, v50, v51
	v_max3_f32 v124, v124, v52, v53
	v_mfma_f32_32x32x16_bf16 v[30:45], v[194:197], v[226:229], v[30:45]
	s_mov_b32 m0, s55
	ds_read_b128 v[194:197], v218 offset:17920
	global_load_lds_dwordx4 v[248:249], off
	v_max3_f32 v125, v125, v54, v55
	v_max3_f32 v124, v124, v56, v57
	v_max3_f32 v125, v125, v58, v59
	v_mfma_f32_32x32x16_bf16 v[14:29], v[198:201], v[230:233], v[14:29]
	ds_read_b128 v[198:201], v218 offset:13344
	v_max3_f32 v124, v124, v60, v61
	v_max3_f32 v125, v125, v62, v63
	v_max3_f32 v124, v124, v64, v65
	v_mfma_f32_32x32x16_bf16 v[30:45], v[202:205], v[230:233], v[30:45]
	ds_read_b128 v[202:205], v218 offset:17952
	v_max3_f32 v125, v125, v66, v67
	v_max3_f32 v124, v124, v68, v69
	v_max3_f32 v125, v125, v70, v71
	v_mfma_f32_32x32x16_bf16 v[14:29], v[206:209], v[234:237], v[14:29]
	ds_read_b128 v[206:209], v218 offset:13376
	v_max3_f32 v124, v124, v72, v73
	v_max3_f32 v125, v125, v74, v75
	v_mfma_f32_32x32x16_bf16 v[30:45], v[210:213], v[234:237], v[30:45]
	ds_read_b128 v[210:213], v218 offset:17984
	v_max3_f32 v124, v124, v76, v77
	v_max_f32_e32 v124, v124, v125
	v_mfma_f32_32x32x16_bf16 v[14:29], v[214:217], v[238:241], v[14:29]
	ds_read_b128 v[214:217], v218 offset:13408
	v_mov_b32_e32 v125, v124
	s_nop 1
	v_mfma_f32_32x32x16_bf16 v[30:45], v[222:225], v[238:241], v[30:45]
	s_waitcnt lgkmcnt(14)
	ds_read_b128 v[222:225], v218 offset:18016
	v_permlane32_swap_b32_e32 v124, v125
	v_max_f32_e32 v126, v124, v125
	v_lshl_add_u64 v[244:245], v[244:245], 0, s[46:47]
	v_lshl_add_u64 v[248:249], v[248:249], 0, s[46:47]
	v_lshl_add_u64 v[250:251], v[250:251], 0, s[48:49]
	s_branch .Lf3_tail4

.Lf3_nocwt3FULLM:
	s_or_b64 exec, exec, s[12:13]
	v_exp_f32_e32 v102, v102
	v_exp_f32_e32 v103, v103
	v_exp_f32_e32 v104, v104
	v_exp_f32_e32 v105, v105
	v_exp_f32_e32 v106, v106
	v_exp_f32_e32 v107, v107
	v_exp_f32_e32 v108, v108
	v_exp_f32_e32 v109, v109
	v_add_f32_e32 v122, v122, v102
	v_add_f32_e32 v123, v123, v103
	v_add_f32_e32 v122, v122, v104
	v_add_f32_e32 v123, v123, v105
	v_add_f32_e32 v122, v122, v106
	v_add_f32_e32 v123, v123, v107
	v_add_f32_e32 v122, v122, v108
	v_add_f32_e32 v123, v123, v109
	v_cvt_pk_bf16_f32 v238, v102, v103
	v_cvt_pk_bf16_f32 v239, v104, v105
	v_cvt_pk_bf16_f32 v240, v106, v107
	v_cvt_pk_bf16_f32 v241, v108, v109
	v_add_f32_e32 v122, v122, v123
	v_add_f32_e32 v161, v161, v122
	s_waitcnt lgkmcnt(0)
	s_barrier
	ds_read_b128 v[78:81], v158 offset:43264
	ds_read_b128 v[82:85], v158 offset:43296
	ds_read_b128 v[86:89], v158 offset:43328
	ds_read_b128 v[90:93], v158 offset:43360
	ds_read_b128 v[94:97], v158 offset:43392
	ds_read_b128 v[98:101], v158 offset:43424
	ds_read_b128 v[102:105], v158 offset:43456
	ds_read_b128 v[106:109], v158 offset:43488
	v_mfma_f32_32x32x16_bf16 v[14:29], v[190:193], v[226:229], v[14:29]
	ds_read_b128 v[190:193], v218 offset:13312
	v_cmp_le_i32_e64 s[52:53], 0, v219
	v_cmp_le_i32_e64 s[14:15], 32, v219
	v_cmp_le_i32_e64 s[16:17], 1, v219
	v_cndmask_b32_e64 v46, v220, v46, s[52:53]
	v_cmp_le_i32_e64 s[52:53], 33, v219
	v_cndmask_b32_e64 v62, v220, v62, s[14:15]
	v_cmp_le_i32_e64 s[14:15], 2, v219
	v_cndmask_b32_e64 v47, v220, v47, s[16:17]
	v_cmp_le_i32_e64 s[16:17], 34, v219
	v_cndmask_b32_e64 v63, v220, v63, s[52:53]
	v_cmp_le_i32_e64 s[52:53], 3, v219
	v_mfma_f32_32x32x16_bf16 v[30:45], v[194:197], v[226:229], v[30:45]
	s_mov_b32 m0, s55
	ds_read_b128 v[194:197], v218 offset:17920
	global_load_lds_dwordx4 v[248:249], off
	v_cndmask_b32_e64 v48, v220, v48, s[14:15]
	v_cmp_le_i32_e64 s[14:15], 35, v219
	v_cndmask_b32_e64 v64, v220, v64, s[16:17]
	v_cmp_le_i32_e64 s[16:17], 8, v219
	v_cndmask_b32_e64 v49, v220, v49, s[52:53]
	v_cmp_le_i32_e64 s[52:53], 40, v219
	v_cndmask_b32_e64 v65, v220, v65, s[14:15]
	v_cmp_le_i32_e64 s[14:15], 9, v219
	v_cndmask_b32_e64 v50, v220, v50, s[16:17]
	v_cmp_le_i32_e64 s[16:17], 41, v219
	v_cndmask_b32_e64 v66, v220, v66, s[52:53]
	v_mfma_f32_32x32x16_bf16 v[14:29], v[198:201], v[230:233], v[14:29]
	ds_read_b128 v[198:201], v218 offset:13344
	v_cmp_le_i32_e64 s[52:53], 10, v219
	v_cndmask_b32_e64 v51, v220, v51, s[14:15]
	v_cmp_le_i32_e64 s[14:15], 42, v219
	v_cndmask_b32_e64 v67, v220, v67, s[16:17]
	v_cmp_le_i32_e64 s[16:17], 11, v219
	v_cndmask_b32_e64 v52, v220, v52, s[52:53]
	v_cmp_le_i32_e64 s[52:53], 43, v219
	v_cndmask_b32_e64 v68, v220, v68, s[14:15]
	v_cmp_le_i32_e64 s[14:15], 16, v219
	v_cndmask_b32_e64 v53, v220, v53, s[16:17]
	v_cmp_le_i32_e64 s[16:17], 48, v219
	v_mfma_f32_32x32x16_bf16 v[30:45], v[202:205], v[230:233], v[30:45]
	ds_read_b128 v[202:205], v218 offset:17952
	v_cndmask_b32_e64 v69, v220, v69, s[52:53]
	v_cmp_le_i32_e64 s[52:53], 17, v219
	v_cndmask_b32_e64 v54, v220, v54, s[14:15]
	v_cmp_le_i32_e64 s[14:15], 49, v219
	v_cndmask_b32_e64 v70, v220, v70, s[16:17]
	v_cmp_le_i32_e64 s[16:17], 18, v219
	v_cndmask_b32_e64 v55, v220, v55, s[52:53]
	v_cmp_le_i32_e64 s[52:53], 50, v219
	v_cndmask_b32_e64 v71, v220, v71, s[14:15]
	v_cmp_le_i32_e64 s[14:15], 19, v219
	v_cndmask_b32_e64 v56, v220, v56, s[16:17]
	v_mfma_f32_32x32x16_bf16 v[14:29], v[206:209], v[234:237], v[14:29]
	ds_read_b128 v[206:209], v218 offset:13376
	v_cmp_le_i32_e64 s[16:17], 51, v219
	v_cndmask_b32_e64 v72, v220, v72, s[52:53]
	v_cmp_le_i32_e64 s[52:53], 24, v219
	v_cndmask_b32_e64 v57, v220, v57, s[14:15]
	v_cmp_le_i32_e64 s[14:15], 56, v219
	v_cndmask_b32_e64 v73, v220, v73, s[16:17]
	v_cmp_le_i32_e64 s[16:17], 25, v219
	v_cndmask_b32_e64 v58, v220, v58, s[52:53]
	v_cmp_le_i32_e64 s[52:53], 57, v219
	v_cndmask_b32_e64 v74, v220, v74, s[14:15]
	v_mfma_f32_32x32x16_bf16 v[30:45], v[210:213], v[234:237], v[30:45]
	ds_read_b128 v[210:213], v218 offset:17984
	v_cmp_le_i32_e64 s[14:15], 26, v219
	v_cndmask_b32_e64 v59, v220, v59, s[16:17]
	v_cmp_le_i32_e64 s[16:17], 58, v219
	v_cndmask_b32_e64 v75, v220, v75, s[52:53]
	v_cmp_le_i32_e64 s[52:53], 27, v219
	v_cndmask_b32_e64 v60, v220, v60, s[14:15]
	v_cmp_le_i32_e64 s[14:15], 59, v219
	v_cndmask_b32_e64 v76, v220, v76, s[16:17]
	v_cndmask_b32_e64 v61, v220, v61, s[52:53]
	v_cndmask_b32_e64 v77, v220, v77, s[14:15]
	v_mfma_f32_32x32x16_bf16 v[14:29], v[214:217], v[238:241], v[14:29]
	ds_read_b128 v[214:217], v218 offset:13408
	v_max3_f32 v124, v46, v47, v48
	v_max3_f32 v125, v49, v50, v51
	v_max3_f32 v124, v124, v52, v53
	v_max3_f32 v125, v125, v54, v55
	v_max3_f32 v124, v124, v56, v57
	v_max3_f32 v125, v125, v58, v59
	v_max3_f32 v124, v124, v60, v61
	v_max3_f32 v125, v125, v62, v63
	v_max3_f32 v124, v124, v64, v65
	v_max3_f32 v125, v125, v66, v67
	v_mfma_f32_32x32x16_bf16 v[30:45], v[222:225], v[238:241], v[30:45]
	s_waitcnt lgkmcnt(14)
	ds_read_b128 v[222:225], v218 offset:18016
	v_max3_f32 v124, v124, v68, v69
	v_max3_f32 v125, v125, v70, v71
	v_max3_f32 v124, v124, v72, v73
	v_max3_f32 v125, v125, v74, v75
	v_max3_f32 v124, v124, v76, v77
	v_max_f32_e32 v124, v124, v125
	v_mov_b32_e32 v125, v124
	s_nop 1
	v_permlane32_swap_b32_e32 v124, v125
	v_max_f32_e32 v126, v124, v125
	v_lshl_add_u64 v[244:245], v[244:245], 0, s[46:47]
	v_lshl_add_u64 v[248:249], v[248:249], 0, s[46:47]
	v_lshl_add_u64 v[250:251], v[250:251], 0, s[48:49]
	s_branch .Lf3_tail4

.Lf3_nocwt3CONLY:
	s_or_b64 exec, exec, s[12:13]
	s_waitcnt lgkmcnt(0)
	s_barrier
	v_mfma_f32_32x32x16_bf16 v[14:29], v[190:193], v[226:229], v[14:29]
	s_mov_b32 m0, s55
	v_mfma_f32_32x32x16_bf16 v[30:45], v[194:197], v[226:229], v[30:45]
	global_load_lds_dwordx4 v[248:249], off
	v_mfma_f32_32x32x16_bf16 v[14:29], v[198:201], v[230:233], v[14:29]
	v_mfma_f32_32x32x16_bf16 v[30:45], v[202:205], v[230:233], v[30:45]
	v_mfma_f32_32x32x16_bf16 v[14:29], v[206:209], v[234:237], v[14:29]
	v_mfma_f32_32x32x16_bf16 v[30:45], v[210:213], v[234:237], v[30:45]
	v_mfma_f32_32x32x16_bf16 v[14:29], v[214:217], v[238:241], v[14:29]
	v_mfma_f32_32x32x16_bf16 v[30:45], v[222:225], v[238:241], v[30:45]
	v_lshl_add_u64 v[244:245], v[244:245], 0, s[46:47]
	v_lshl_add_u64 v[248:249], v[248:249], 0, s[46:47]
	v_lshl_add_u64 v[250:251], v[250:251], 0, s[48:49]

.Lm3_nokrp:
	s_mov_b32 m0, s15
	s_or_b64 exec, exec, s[4:5]
	global_load_lds_dwordx4 v227, s[54:55]
	s_add_u32 s54, s54, 0x10000
	s_addc_u32 s55, s55, 0
	s_add_u32 s56, s56, 0x1000
	s_addc_u32 s57, s57, 0
	ds_read_b128 v[134:137], v162 offset:13312
	ds_read_b128 v[138:141], v162 offset:19968
	ds_read_b128 v[142:145], v162 offset:13344
	ds_read_b128 v[168:171], v162 offset:20000
	ds_read_b128 v[172:175], v162 offset:13376
	ds_read_b128 v[178:181], v162 offset:20032
	ds_read_b128 v[182:185], v162 offset:13408
	ds_read_b128 v[186:189], v162 offset:20064
	ds_read_b128 v[206:209], v162 offset:13440
	ds_read_b128 v[210:213], v162 offset:20096
	ds_read_b128 v[214:217], v162 offset:13472
	ds_read_b128 v[248:251], v162 offset:20128
	v_max3_f32 v240, v46, v47, v48
	v_max3_f32 v241, v49, v50, v51
	v_max3_f32 v240, v240, v52, v53
	v_max3_f32 v241, v241, v54, v55
	v_max3_f32 v240, v240, v56, v57
	v_max3_f32 v241, v241, v58, v59
	v_max3_f32 v240, v240, v60, v61
	v_max3_f32 v241, v241, v62, v63
	v_max3_f32 v240, v240, v64, v65
	v_max3_f32 v241, v241, v66, v67
	v_max3_f32 v240, v240, v68, v69
	v_max3_f32 v241, v241, v70, v71
	v_max3_f32 v240, v240, v72, v73
	v_max3_f32 v241, v241, v74, v75
	v_max3_f32 v240, v240, v76, v77
	v_max_f32_e32 v240, v240, v241
	v_mov_b32_e32 v241, v240
	s_nop 1
	v_permlane32_swap_b32_e32 v240, v241
	v_max_f32_e32 v244, v240, v241
	v_mov_b32_e32 v164, v244
	v_sub_f32_e32 v190, 0, v244
	v_mov_b32_e32 v191, v190
	v_mov_b32_e32 v192, v190
	v_mov_b32_e32 v193, v190
	v_mov_b32_e32 v194, v190
	v_mov_b32_e32 v195, v190
	v_mov_b32_e32 v196, v190
	v_mov_b32_e32 v197, v190
	v_mov_b32_e32 v198, v190
	v_mov_b32_e32 v199, v190
	v_mov_b32_e32 v200, v190
	v_mov_b32_e32 v201, v190
	v_mov_b32_e32 v202, v190
	v_mov_b32_e32 v203, v190
	v_mov_b32_e32 v204, v190
	v_mov_b32_e32 v205, v190
	v_sub_f32_e32 v46, v46, v164
	v_sub_f32_e32 v47, v47, v164
	v_sub_f32_e32 v48, v48, v164
	v_sub_f32_e32 v49, v49, v164
	v_sub_f32_e32 v50, v50, v164
	v_sub_f32_e32 v51, v51, v164
	v_sub_f32_e32 v52, v52, v164
	v_sub_f32_e32 v53, v53, v164
	v_sub_f32_e32 v54, v54, v164
	v_sub_f32_e32 v55, v55, v164
	v_sub_f32_e32 v56, v56, v164
	v_sub_f32_e32 v57, v57, v164
	v_sub_f32_e32 v58, v58, v164
	v_sub_f32_e32 v59, v59, v164
	v_sub_f32_e32 v60, v60, v164
	v_sub_f32_e32 v61, v61, v164
	v_sub_f32_e32 v62, v62, v164
	v_sub_f32_e32 v63, v63, v164
	v_sub_f32_e32 v64, v64, v164
	v_sub_f32_e32 v65, v65, v164
	v_sub_f32_e32 v66, v66, v164
	v_sub_f32_e32 v67, v67, v164
	v_sub_f32_e32 v68, v68, v164
	v_sub_f32_e32 v69, v69, v164
	v_sub_f32_e32 v70, v70, v164
	v_sub_f32_e32 v71, v71, v164
	v_sub_f32_e32 v72, v72, v164
	v_sub_f32_e32 v73, v73, v164
	v_sub_f32_e32 v74, v74, v164
	v_sub_f32_e32 v75, v75, v164
	v_sub_f32_e32 v76, v76, v164
	v_sub_f32_e32 v77, v77, v164
	v_mov_b32_e32 v244, 0
	s_lshr_b32 s11, s33, 1
	s_mov_b32 s10, 0
	s_cmp_le_u32 s35, 4
	s_cbranch_scc1 .Lm3_tail0

.Lm3_nokra:
	s_or_b64 exec, exec, s[4:5]
	v_cvt_pk_bf16_f32 v232, v66, v67
	v_cvt_pk_bf16_f32 v233, v68, v69
	v_add_f32_e32 v238, v238, v66
	v_add_f32_e32 v239, v239, v67
	v_add_f32_e32 v242, v242, v68
	v_add_f32_e32 v243, v243, v69
	v_mfma_f32_32x32x16_bf16 v[14:29], v[142:145], v[222:225], v[14:29]
	ds_read_b128 v[142:145], v162 offset:32
	v_cvt_pk_bf16_f32 v234, v70, v71
	v_cvt_pk_bf16_f32 v235, v72, v73
	v_cvt_pk_bf16_f32 v236, v74, v75
	v_cvt_pk_bf16_f32 v237, v76, v77
	v_add_f32_e32 v238, v238, v70
	v_add_f32_e32 v239, v239, v71
	v_mfma_f32_32x32x16_bf16 v[30:45], v[168:171], v[222:225], v[30:45]
	ds_read_b128 v[168:171], v162 offset:6688
	v_add_f32_e32 v242, v242, v72
	v_add_f32_e32 v243, v243, v73
	v_add_f32_e32 v238, v238, v74
	v_add_f32_e32 v239, v239, v75
	v_add_f32_e32 v242, v242, v76
	v_add_f32_e32 v243, v243, v77
	v_add_f32_e32 v238, v238, v239
	v_mfma_f32_32x32x16_bf16 v[14:29], v[172:175], v[230:233], v[14:29]
	ds_read_b128 v[172:175], v162 offset:64
	v_add_f32_e32 v242, v242, v243
	v_add_f32_e32 v238, v238, v242
	v_add_f32_e32 v165, v165, v238
	v_max3_f32 v240, v78, v79, v80
	v_max3_f32 v241, v81, v82, v83
	v_max3_f32 v240, v240, v84, v85
	v_mfma_f32_32x32x16_bf16 v[30:45], v[178:181], v[230:233], v[30:45]
	s_mov_b32 m0, s14
	ds_read_b128 v[178:181], v162 offset:6720
	global_load_lds_dwordx4 v227, s[54:55]
	v_max3_f32 v241, v241, v86, v87
	v_max3_f32 v240, v240, v88, v89
	v_max3_f32 v241, v241, v90, v91
	v_max3_f32 v240, v240, v92, v93
	v_max3_f32 v241, v241, v94, v95
	v_max3_f32 v240, v240, v96, v97
	v_mfma_f32_32x32x16_bf16 v[14:29], v[182:185], v[234:237], v[14:29]
	ds_read_b128 v[182:185], v162 offset:96
	v_max3_f32 v241, v241, v98, v99
	v_max3_f32 v240, v240, v100, v101
	v_max3_f32 v241, v241, v102, v103
	v_max3_f32 v240, v240, v104, v105
	v_max3_f32 v241, v241, v106, v107
	v_mfma_f32_32x32x16_bf16 v[30:45], v[186:189], v[234:237], v[30:45]
	ds_read_b128 v[186:189], v162 offset:6752
	v_max3_f32 v240, v240, v108, v109
	v_max_f32_e32 v240, v240, v241
	v_mov_b32_e32 v241, v240
	s_nop 1
	v_permlane32_swap_b32_e32 v240, v241
	v_max_f32_e32 v244, v240, v241
	s_add_u32 s54, s54, 0x10000
	s_addc_u32 s55, s55, 0
	s_add_u32 s56, s56, 0x1000
	s_addc_u32 s57, s57, 0
	v_cmp_lt_f32_e32 vcc, 0x41800000, v244
	s_cbranch_vccnz .Lm3_rescb

.Lm3_nokrb:
	s_or_b64 exec, exec, s[4:5]
	v_cvt_pk_bf16_f32 v232, v98, v99
	v_cvt_pk_bf16_f32 v233, v100, v101
	v_add_f32_e32 v238, v238, v98
	v_add_f32_e32 v239, v239, v99
	v_add_f32_e32 v242, v242, v100
	v_add_f32_e32 v243, v243, v101
	v_mfma_f32_32x32x16_bf16 v[14:29], v[142:145], v[222:225], v[14:29]
	ds_read_b128 v[142:145], v162 offset:13344
	v_cvt_pk_bf16_f32 v234, v102, v103
	v_cvt_pk_bf16_f32 v235, v104, v105
	v_cvt_pk_bf16_f32 v236, v106, v107
	v_cvt_pk_bf16_f32 v237, v108, v109
	v_add_f32_e32 v238, v238, v102
	v_add_f32_e32 v239, v239, v103
	v_mfma_f32_32x32x16_bf16 v[30:45], v[168:171], v[222:225], v[30:45]
	ds_read_b128 v[168:171], v162 offset:20000
	v_add_f32_e32 v242, v242, v104
	v_add_f32_e32 v243, v243, v105
	v_add_f32_e32 v238, v238, v106
	v_add_f32_e32 v239, v239, v107
	v_add_f32_e32 v242, v242, v108
	v_add_f32_e32 v243, v243, v109
	v_add_f32_e32 v238, v238, v239
	v_mfma_f32_32x32x16_bf16 v[14:29], v[172:175], v[230:233], v[14:29]
	ds_read_b128 v[172:175], v162 offset:13376
	v_add_f32_e32 v242, v242, v243
	v_add_f32_e32 v238, v238, v242
	v_add_f32_e32 v165, v165, v238
	v_max3_f32 v240, v46, v47, v48
	v_max3_f32 v241, v49, v50, v51
	v_max3_f32 v240, v240, v52, v53
	v_mfma_f32_32x32x16_bf16 v[30:45], v[178:181], v[230:233], v[30:45]
	s_mov_b32 m0, s15
	ds_read_b128 v[178:181], v162 offset:20032
	global_load_lds_dwordx4 v227, s[54:55]
	v_max3_f32 v241, v241, v54, v55
	v_max3_f32 v240, v240, v56, v57
	v_max3_f32 v241, v241, v58, v59
	v_max3_f32 v240, v240, v60, v61
	v_max3_f32 v241, v241, v62, v63
	v_max3_f32 v240, v240, v64, v65
	v_mfma_f32_32x32x16_bf16 v[14:29], v[182:185], v[234:237], v[14:29]
	ds_read_b128 v[182:185], v162 offset:13408
	v_max3_f32 v241, v241, v66, v67
	v_max3_f32 v240, v240, v68, v69
	v_max3_f32 v241, v241, v70, v71
	v_max3_f32 v240, v240, v72, v73
	v_max3_f32 v241, v241, v74, v75
	v_mfma_f32_32x32x16_bf16 v[30:45], v[186:189], v[234:237], v[30:45]
	ds_read_b128 v[186:189], v162 offset:20064
	v_max3_f32 v240, v240, v76, v77
	v_max_f32_e32 v240, v240, v241
	v_mov_b32_e32 v241, v240
	s_nop 1
	v_permlane32_swap_b32_e32 v240, v241
	v_max_f32_e32 v244, v240, v241
	s_add_u32 s54, s54, 0x10000
	s_addc_u32 s55, s55, 0
	s_add_u32 s56, s56, 0x1000
	s_addc_u32 s57, s57, 0
	s_add_i32 s10, s10, 2
	s_add_i32 s4, s10, 4
	s_cmp_lt_u32 s4, s35
	s_cbranch_scc1 .Lm3_loop

.Lm3_nokrt0i:
	s_mov_b32 m0, s14
	s_or_b64 exec, exec, s[4:5]
	global_load_lds_dwordx4 v227, s[54:55]
	s_add_u32 s54, s54, 0x10000
	s_addc_u32 s55, s55, 0
	s_add_u32 s56, s56, 0x1000
	s_addc_u32 s57, s57, 0
	s_branch .Lm3_tail1

.Lm3_nokrt0l:
	s_or_b64 exec, exec, s[4:5]
	v_cvt_pk_bf16_f32 v225, v60, v61
	v_cvt_pk_bf16_f32 v230, v62, v63
	v_cvt_pk_bf16_f32 v231, v64, v65
	v_mfma_f32_32x32x16_bf16 v[14:29], v[142:145], v[222:225], v[14:29]
	v_cvt_pk_bf16_f32 v232, v66, v67
	v_cvt_pk_bf16_f32 v233, v68, v69
	v_add_f32_e32 v238, v238, v66
	v_mfma_f32_32x32x16_bf16 v[30:45], v[168:171], v[222:225], v[30:45]
	v_add_f32_e32 v239, v239, v67
	v_add_f32_e32 v242, v242, v68
	v_add_f32_e32 v243, v243, v69
	v_cvt_pk_bf16_f32 v234, v70, v71
	v_mfma_f32_32x32x16_bf16 v[14:29], v[172:175], v[230:233], v[14:29]
	v_cvt_pk_bf16_f32 v235, v72, v73
	v_cvt_pk_bf16_f32 v236, v74, v75
	v_cvt_pk_bf16_f32 v237, v76, v77
	s_mov_b32 m0, s14
	v_mfma_f32_32x32x16_bf16 v[30:45], v[178:181], v[230:233], v[30:45]
	global_load_lds_dwordx4 v227, s[54:55]
	v_add_f32_e32 v238, v238, v70
	v_add_f32_e32 v239, v239, v71
	v_add_f32_e32 v242, v242, v72
	v_add_f32_e32 v243, v243, v73
	v_mfma_f32_32x32x16_bf16 v[14:29], v[182:185], v[234:237], v[14:29]
	v_add_f32_e32 v238, v238, v74
	v_add_f32_e32 v239, v239, v75
	v_add_f32_e32 v242, v242, v76
	v_add_f32_e32 v243, v243, v77
	v_mfma_f32_32x32x16_bf16 v[30:45], v[186:189], v[234:237], v[30:45]
	v_add_f32_e32 v238, v238, v239
	v_add_f32_e32 v242, v242, v243
	v_add_f32_e32 v238, v238, v242
	v_add_f32_e32 v165, v165, v238
	s_add_u32 s54, s54, 0x10000
	s_addc_u32 s55, s55, 0
	s_add_u32 s56, s56, 0x1000
	s_addc_u32 s57, s57, 0
	s_branch .Lm3_tail1

.Lm3_nokrt0f:
	s_or_b64 exec, exec, s[4:5]
	v_cvt_pk_bf16_f32 v232, v66, v67
	v_cvt_pk_bf16_f32 v233, v68, v69
	v_add_f32_e32 v238, v238, v66
	v_add_f32_e32 v239, v239, v67
	v_add_f32_e32 v242, v242, v68
	v_add_f32_e32 v243, v243, v69
	v_mfma_f32_32x32x16_bf16 v[14:29], v[142:145], v[222:225], v[14:29]
	ds_read_b128 v[142:145], v162 offset:32
	v_cvt_pk_bf16_f32 v234, v70, v71
	v_cvt_pk_bf16_f32 v235, v72, v73
	v_cvt_pk_bf16_f32 v236, v74, v75
	v_cvt_pk_bf16_f32 v237, v76, v77
	v_add_f32_e32 v238, v238, v70
	v_add_f32_e32 v239, v239, v71
	v_mfma_f32_32x32x16_bf16 v[30:45], v[168:171], v[222:225], v[30:45]
	ds_read_b128 v[168:171], v162 offset:6688
	v_add_f32_e32 v242, v242, v72
	v_add_f32_e32 v243, v243, v73
	v_add_f32_e32 v238, v238, v74
	v_add_f32_e32 v239, v239, v75
	v_add_f32_e32 v242, v242, v76
	v_add_f32_e32 v243, v243, v77
	v_add_f32_e32 v238, v238, v239
	v_mfma_f32_32x32x16_bf16 v[14:29], v[172:175], v[230:233], v[14:29]
	ds_read_b128 v[172:175], v162 offset:64
	v_add_f32_e32 v242, v242, v243
	v_add_f32_e32 v238, v238, v242
	v_add_f32_e32 v165, v165, v238
	v_max3_f32 v240, v78, v79, v80
	v_max3_f32 v241, v81, v82, v83
	v_max3_f32 v240, v240, v84, v85
	v_mfma_f32_32x32x16_bf16 v[30:45], v[178:181], v[230:233], v[30:45]
	s_mov_b32 m0, s14
	ds_read_b128 v[178:181], v162 offset:6720
	global_load_lds_dwordx4 v227, s[54:55]
	v_max3_f32 v241, v241, v86, v87
	v_max3_f32 v240, v240, v88, v89
	v_max3_f32 v241, v241, v90, v91
	v_max3_f32 v240, v240, v92, v93
	v_max3_f32 v241, v241, v94, v95
	v_max3_f32 v240, v240, v96, v97
	v_mfma_f32_32x32x16_bf16 v[14:29], v[182:185], v[234:237], v[14:29]
	ds_read_b128 v[182:185], v162 offset:96
	v_max3_f32 v241, v241, v98, v99
	v_max3_f32 v240, v240, v100, v101
	v_max3_f32 v241, v241, v102, v103
	v_max3_f32 v240, v240, v104, v105
	v_max3_f32 v241, v241, v106, v107
	v_mfma_f32_32x32x16_bf16 v[30:45], v[186:189], v[234:237], v[30:45]
	ds_read_b128 v[186:189], v162 offset:6752
	v_max3_f32 v240, v240, v108, v109
	v_max_f32_e32 v240, v240, v241
	v_mov_b32_e32 v241, v240
	s_nop 1
	v_permlane32_swap_b32_e32 v240, v241
	v_max_f32_e32 v244, v240, v241
	s_add_u32 s54, s54, 0x10000
	s_addc_u32 s55, s55, 0
	s_add_u32 s56, s56, 0x1000
	s_addc_u32 s57, s57, 0

.Lm3_nokwt1l:
	s_or_b64 exec, exec, s[4:5]
	s_waitcnt lgkmcnt(0)
	s_barrier
	v_mfma_f32_32x32x16_bf16 v[14:29], v[134:137], v[152:155], v[14:29]
	v_cvt_pk_bf16_f32 v222, v86, v87
	v_cvt_pk_bf16_f32 v223, v88, v89
	v_cvt_pk_bf16_f32 v224, v90, v91
	v_mfma_f32_32x32x16_bf16 v[30:45], v[138:141], v[152:155], v[30:45]
	v_cvt_pk_bf16_f32 v225, v92, v93
	v_cvt_pk_bf16_f32 v230, v94, v95
	v_cvt_pk_bf16_f32 v231, v96, v97
	v_mfma_f32_32x32x16_bf16 v[14:29], v[142:145], v[222:225], v[14:29]
	v_cvt_pk_bf16_f32 v232, v98, v99
	v_cvt_pk_bf16_f32 v233, v100, v101
	v_add_f32_e32 v238, v238, v98
	v_mfma_f32_32x32x16_bf16 v[30:45], v[168:171], v[222:225], v[30:45]
	v_add_f32_e32 v239, v239, v99
	v_add_f32_e32 v242, v242, v100
	v_add_f32_e32 v243, v243, v101
	v_cvt_pk_bf16_f32 v234, v102, v103
	v_mfma_f32_32x32x16_bf16 v[14:29], v[172:175], v[230:233], v[14:29]
	v_cvt_pk_bf16_f32 v235, v104, v105
	v_cvt_pk_bf16_f32 v236, v106, v107
	v_cvt_pk_bf16_f32 v237, v108, v109
	s_mov_b32 m0, s15
	v_mfma_f32_32x32x16_bf16 v[30:45], v[178:181], v[230:233], v[30:45]
	global_load_lds_dwordx4 v227, s[54:55]
	v_add_f32_e32 v238, v238, v102
	v_add_f32_e32 v239, v239, v103
	v_add_f32_e32 v242, v242, v104
	v_add_f32_e32 v243, v243, v105
	v_mfma_f32_32x32x16_bf16 v[14:29], v[182:185], v[234:237], v[14:29]
	v_add_f32_e32 v238, v238, v106
	v_add_f32_e32 v239, v239, v107
	v_add_f32_e32 v242, v242, v108
	v_add_f32_e32 v243, v243, v109
	v_mfma_f32_32x32x16_bf16 v[30:45], v[186:189], v[234:237], v[30:45]
	v_add_f32_e32 v238, v238, v239
	v_add_f32_e32 v242, v242, v243
	v_add_f32_e32 v238, v238, v242
	v_add_f32_e32 v165, v165, v238
	s_add_u32 s54, s54, 0x10000
	s_addc_u32 s55, s55, 0
	s_add_u32 s56, s56, 0x1000
	s_addc_u32 s57, s57, 0
	s_branch .Lm3_tail2

.Lm3_nokwt1f:
	s_or_b64 exec, exec, s[4:5]
	v_mfma_f32_32x32x16_bf16 v[62:77], v[210:213], v[114:117], v[62:77]
	v_add_f32_e32 v243, v243, v93
	v_exp_f32_e32 v102, v102
	v_exp_f32_e32 v103, v103
	v_exp_f32_e32 v104, v104
	v_mfma_f32_32x32x16_bf16 v[46:61], v[214:217], v[118:121], v[46:61]
	v_exp_f32_e32 v105, v105
	v_exp_f32_e32 v106, v106
	v_exp_f32_e32 v107, v107
	v_exp_f32_e32 v108, v108
	v_mfma_f32_32x32x16_bf16 v[62:77], v[248:251], v[118:121], v[62:77]
	v_exp_f32_e32 v109, v109
	v_add_f32_e32 v238, v238, v94
	v_add_f32_e32 v239, v239, v95
	v_add_f32_e32 v242, v242, v96
	v_add_f32_e32 v243, v243, v97
	s_waitcnt lgkmcnt(0)
	s_barrier
	ds_read_b128 v[206:209], v162 offset:13440
	ds_read_b128 v[210:213], v162 offset:20096
	ds_read_b128 v[214:217], v162 offset:13472
	ds_read_b128 v[248:251], v162 offset:20128
	v_mfma_f32_32x32x16_bf16 v[14:29], v[134:137], v[152:155], v[14:29]
	ds_read_b128 v[134:137], v162 offset:13312
	v_cvt_pk_bf16_f32 v222, v86, v87
	v_cvt_pk_bf16_f32 v223, v88, v89
	v_cvt_pk_bf16_f32 v224, v90, v91
	v_cvt_pk_bf16_f32 v225, v92, v93
	v_cvt_pk_bf16_f32 v230, v94, v95
	v_cvt_pk_bf16_f32 v231, v96, v97
	v_mfma_f32_32x32x16_bf16 v[30:45], v[138:141], v[152:155], v[30:45]
	ds_read_b128 v[138:141], v162 offset:19968
	v_cvt_pk_bf16_f32 v232, v98, v99
	v_cvt_pk_bf16_f32 v233, v100, v101
	v_add_f32_e32 v238, v238, v98
	v_add_f32_e32 v239, v239, v99
	v_add_f32_e32 v242, v242, v100
	v_add_f32_e32 v243, v243, v101
	v_mfma_f32_32x32x16_bf16 v[14:29], v[142:145], v[222:225], v[14:29]
	ds_read_b128 v[142:145], v162 offset:13344
	v_cvt_pk_bf16_f32 v234, v102, v103
	v_cvt_pk_bf16_f32 v235, v104, v105
	v_cvt_pk_bf16_f32 v236, v106, v107
	v_cvt_pk_bf16_f32 v237, v108, v109
	v_add_f32_e32 v238, v238, v102
	v_add_f32_e32 v239, v239, v103
	v_mfma_f32_32x32x16_bf16 v[30:45], v[168:171], v[222:225], v[30:45]
	ds_read_b128 v[168:171], v162 offset:20000
	v_add_f32_e32 v242, v242, v104
	v_add_f32_e32 v243, v243, v105
	v_add_f32_e32 v238, v238, v106
	v_add_f32_e32 v239, v239, v107
	v_add_f32_e32 v242, v242, v108
	v_add_f32_e32 v243, v243, v109
	v_add_f32_e32 v238, v238, v239
	v_mfma_f32_32x32x16_bf16 v[14:29], v[172:175], v[230:233], v[14:29]
	ds_read_b128 v[172:175], v162 offset:13376
	v_add_f32_e32 v242, v242, v243
	v_add_f32_e32 v238, v238, v242
	v_add_f32_e32 v165, v165, v238
	v_max3_f32 v240, v46, v47, v48
	v_max3_f32 v241, v49, v50, v51
	v_max3_f32 v240, v240, v52, v53
	v_mfma_f32_32x32x16_bf16 v[30:45], v[178:181], v[230:233], v[30:45]
	s_mov_b32 m0, s15
	ds_read_b128 v[178:181], v162 offset:20032
	global_load_lds_dwordx4 v227, s[54:55]
	v_max3_f32 v241, v241, v54, v55
	v_max3_f32 v240, v240, v56, v57
	v_max3_f32 v241, v241, v58, v59
	v_max3_f32 v240, v240, v60, v61
	v_max3_f32 v241, v241, v62, v63
	v_max3_f32 v240, v240, v64, v65
	v_mfma_f32_32x32x16_bf16 v[14:29], v[182:185], v[234:237], v[14:29]
	ds_read_b128 v[182:185], v162 offset:13408
	v_max3_f32 v241, v241, v66, v67
	v_max3_f32 v240, v240, v68, v69
	v_max3_f32 v241, v241, v70, v71
	v_max3_f32 v240, v240, v72, v73
	v_max3_f32 v241, v241, v74, v75
	v_mfma_f32_32x32x16_bf16 v[30:45], v[186:189], v[234:237], v[30:45]
	ds_read_b128 v[186:189], v162 offset:20064
	v_max3_f32 v240, v240, v76, v77
	v_max_f32_e32 v240, v240, v241
	v_mov_b32_e32 v241, v240
	s_nop 1
	v_permlane32_swap_b32_e32 v240, v241
	v_max_f32_e32 v244, v240, v241
	s_add_u32 s54, s54, 0x10000
	s_addc_u32 s55, s55, 0
	s_add_u32 s56, s56, 0x1000
	s_addc_u32 s57, s57, 0
